# GEMM K-loops: removed the no-op s_setprio 0/1 toggle in the middle of each MFMA block (MFMA half is the critical barrier arriver per delay probes)
# speedup vs baseline: 1.0079x; 1.0079x over previous
.LBB0_168:
	s_add_u32 s46, s66, 0xfff80080
	s_addc_u32 s47, s67, -1
	s_add_i32 s62, 0, 0x10000
	s_cmp_eq_u32 s82, 28
	s_cselect_b32 s69, s17, s47
	s_cselect_b32 s68, s65, s46
	v_add_u32_e32 v143, s62, v140
	s_cselect_b32 s61, s13, s81
	s_cselect_b32 s60, s79, s80
	s_add_i32 s63, 0, 0x14000
	ds_read_b128 v[144:147], v143
	ds_read_b128 v[148:151], v143 offset:1024
	ds_read_b128 v[152:155], v143 offset:2048
	ds_read_b128 v[156:159], v143 offset:3072
	v_add_u32_e32 v143, s63, v140
	ds_read_b128 v[160:163], v143
	ds_read_b128 v[178:181], v143 offset:1024
	ds_read_b128 v[182:185], v143 offset:2048
	ds_read_b128 v[186:189], v143 offset:3072
	v_lshl_add_u64 v[164:165], s[66:67], 0, v[136:137]
	s_add_i32 m0, s19, 0xc000
	ds_read_b128 v[206:209], v142
	ds_read_b128 v[210:213], v142 offset:1024
	ds_read_b128 v[214:217], v142 offset:2048
	ds_read_b128 v[218:221], v142 offset:3072
	ds_read_b128 v[222:225], v142 offset:4096
	ds_read_b128 v[226:229], v142 offset:5120
	ds_read_b128 v[230:233], v142 offset:6144
	ds_read_b128 v[234:237], v142 offset:7168
	global_load_lds_dwordx4 v[164:165], off
	v_lshl_add_u64 v[164:165], s[66:67], 0, v[138:139]
	s_add_i32 m0, s19, 0xe000
	s_nop 0
	global_load_lds_dwordx4 v[164:165], off
	s_waitcnt vmcnt(8)
	s_waitcnt lgkmcnt(0)
	s_setprio 1
	s_waitcnt lgkmcnt(0)
	v_mfma_f32_16x16x32_bf16 v[126:129], v[144:147], v[206:209], v[126:129]
	v_mfma_f32_16x16x32_bf16 v[122:125], v[152:155], v[206:209], v[122:125]
	v_mfma_f32_16x16x32_bf16 v[118:121], v[144:147], v[214:217], v[118:121]
	v_mfma_f32_16x16x32_bf16 v[114:117], v[152:155], v[214:217], v[114:117]
	s_barrier
	v_mfma_f32_16x16x32_bf16 v[102:105], v[144:147], v[222:225], v[102:105]
	v_mfma_f32_16x16x32_bf16 v[98:101], v[152:155], v[222:225], v[98:101]
	v_mfma_f32_16x16x32_bf16 v[86:89], v[144:147], v[230:233], v[86:89]
	v_mfma_f32_16x16x32_bf16 v[82:85], v[152:155], v[230:233], v[82:85]
	v_mfma_f32_16x16x32_bf16 v[126:129], v[148:151], v[210:213], v[126:129]
	v_mfma_f32_16x16x32_bf16 v[122:125], v[156:159], v[210:213], v[122:125]
	v_mfma_f32_16x16x32_bf16 v[118:121], v[148:151], v[218:221], v[118:121]
	v_mfma_f32_16x16x32_bf16 v[114:117], v[156:159], v[218:221], v[114:117]
	v_mfma_f32_16x16x32_bf16 v[102:105], v[148:151], v[226:229], v[102:105]
	v_mfma_f32_16x16x32_bf16 v[98:101], v[156:159], v[226:229], v[98:101]
	v_mfma_f32_16x16x32_bf16 v[86:89], v[148:151], v[234:237], v[86:89]
	v_mfma_f32_16x16x32_bf16 v[82:85], v[156:159], v[234:237], v[82:85]
	v_mfma_f32_16x16x32_bf16 v[110:113], v[160:163], v[206:209], v[110:113]
	v_mfma_f32_16x16x32_bf16 v[106:109], v[182:185], v[206:209], v[106:109]
	v_mfma_f32_16x16x32_bf16 v[94:97], v[160:163], v[214:217], v[94:97]
	v_mfma_f32_16x16x32_bf16 v[90:93], v[182:185], v[214:217], v[90:93]
	v_mfma_f32_16x16x32_bf16 v[78:81], v[160:163], v[222:225], v[78:81]
	v_mfma_f32_16x16x32_bf16 v[74:77], v[182:185], v[222:225], v[74:77]
	v_mfma_f32_16x16x32_bf16 v[70:73], v[160:163], v[230:233], v[70:73]
	v_mfma_f32_16x16x32_bf16 v[66:69], v[182:185], v[230:233], v[66:69]
	v_mfma_f32_16x16x32_bf16 v[110:113], v[178:181], v[210:213], v[110:113]
	v_mfma_f32_16x16x32_bf16 v[106:109], v[186:189], v[210:213], v[106:109]
	v_mfma_f32_16x16x32_bf16 v[94:97], v[178:181], v[218:221], v[94:97]
	v_mfma_f32_16x16x32_bf16 v[90:93], v[186:189], v[218:221], v[90:93]
	v_mfma_f32_16x16x32_bf16 v[78:81], v[178:181], v[226:229], v[78:81]
	v_mfma_f32_16x16x32_bf16 v[74:77], v[186:189], v[226:229], v[74:77]
	v_mfma_f32_16x16x32_bf16 v[70:73], v[178:181], v[234:237], v[70:73]
	v_mfma_f32_16x16x32_bf16 v[66:69], v[186:189], v[234:237], v[66:69]
	s_barrier
	s_setprio 0
	s_add_i32 s46, s62, s71
	v_lshl_add_u64 v[164:165], s[60:61], 0, v[166:167]
	s_mov_b32 m0, s46
	ds_read_b128 v[206:209], v142 offset:16384
	ds_read_b128 v[210:213], v142 offset:17408
	ds_read_b128 v[214:217], v142 offset:18432
	ds_read_b128 v[218:221], v142 offset:19456
	ds_read_b128 v[222:225], v142 offset:20480
	ds_read_b128 v[226:229], v142 offset:21504
	ds_read_b128 v[230:233], v142 offset:22528
	ds_read_b128 v[234:237], v142 offset:23552
	global_load_lds_dwordx4 v[164:165], off
	s_add_i32 m0, s46, 0x2000
	s_add_u32 s46, s60, 0x80000
	v_lshl_add_u64 v[242:243], s[60:61], 0, v[130:131]
	s_addc_u32 s47, s61, 0
	s_add_i32 s62, s63, s71
	global_load_lds_dwordx4 v[242:243], off
	v_lshl_add_u64 v[244:245], s[46:47], 0, v[166:167]
	s_mov_b32 m0, s62
	v_lshl_add_u64 v[246:247], s[68:69], 0, v[132:133]
	global_load_lds_dwordx4 v[244:245], off
	v_lshl_add_u64 v[244:245], s[46:47], 0, v[130:131]
	s_add_i32 m0, s62, 0x2000
	s_nop 0
	global_load_lds_dwordx4 v[244:245], off
	v_lshl_add_u64 v[244:245], s[68:69], 0, v[134:135]
	s_mov_b32 m0, s19
	s_nop 0
	global_load_lds_dwordx4 v[244:245], off
	s_mov_b32 m0, s73
	s_nop 0
	global_load_lds_dwordx4 v[246:247], off
	s_waitcnt vmcnt(8)
	s_waitcnt lgkmcnt(0)
	s_setprio 1
	s_waitcnt lgkmcnt(0)
	v_mfma_f32_16x16x32_bf16 v[62:65], v[144:147], v[206:209], v[62:65]
	v_mfma_f32_16x16x32_bf16 v[58:61], v[152:155], v[206:209], v[58:61]
	v_mfma_f32_16x16x32_bf16 v[54:57], v[144:147], v[214:217], v[54:57]
	v_mfma_f32_16x16x32_bf16 v[50:53], v[152:155], v[214:217], v[50:53]
	s_barrier
	v_mfma_f32_16x16x32_bf16 v[38:41], v[144:147], v[222:225], v[38:41]
	v_mfma_f32_16x16x32_bf16 v[34:37], v[152:155], v[222:225], v[34:37]
	v_mfma_f32_16x16x32_bf16 v[22:25], v[144:147], v[230:233], v[22:25]
	v_mfma_f32_16x16x32_bf16 v[18:21], v[152:155], v[230:233], v[18:21]
	v_mfma_f32_16x16x32_bf16 v[62:65], v[148:151], v[210:213], v[62:65]
	v_mfma_f32_16x16x32_bf16 v[58:61], v[156:159], v[210:213], v[58:61]
	v_mfma_f32_16x16x32_bf16 v[54:57], v[148:151], v[218:221], v[54:57]
	v_mfma_f32_16x16x32_bf16 v[50:53], v[156:159], v[218:221], v[50:53]
	v_mfma_f32_16x16x32_bf16 v[38:41], v[148:151], v[226:229], v[38:41]
	v_mfma_f32_16x16x32_bf16 v[34:37], v[156:159], v[226:229], v[34:37]
	v_mfma_f32_16x16x32_bf16 v[22:25], v[148:151], v[234:237], v[22:25]
	v_mfma_f32_16x16x32_bf16 v[18:21], v[156:159], v[234:237], v[18:21]
	v_mfma_f32_16x16x32_bf16 v[46:49], v[160:163], v[206:209], v[46:49]
	v_mfma_f32_16x16x32_bf16 v[42:45], v[182:185], v[206:209], v[42:45]
	v_mfma_f32_16x16x32_bf16 v[30:33], v[160:163], v[214:217], v[30:33]
	v_mfma_f32_16x16x32_bf16 v[26:29], v[182:185], v[214:217], v[26:29]
	v_mfma_f32_16x16x32_bf16 v[14:17], v[160:163], v[222:225], v[14:17]
	v_mfma_f32_16x16x32_bf16 v[10:13], v[182:185], v[222:225], v[10:13]
	v_mfma_f32_16x16x32_bf16 v[6:9], v[160:163], v[230:233], v[6:9]
	v_mfma_f32_16x16x32_bf16 v[2:5], v[182:185], v[230:233], v[2:5]
	v_mfma_f32_16x16x32_bf16 v[46:49], v[178:181], v[210:213], v[46:49]
	v_mfma_f32_16x16x32_bf16 v[42:45], v[186:189], v[210:213], v[42:45]
	v_mfma_f32_16x16x32_bf16 v[30:33], v[178:181], v[218:221], v[30:33]
	v_mfma_f32_16x16x32_bf16 v[26:29], v[186:189], v[218:221], v[26:29]
	v_mfma_f32_16x16x32_bf16 v[14:17], v[178:181], v[226:229], v[14:17]
	v_mfma_f32_16x16x32_bf16 v[10:13], v[186:189], v[226:229], v[10:13]
	v_mfma_f32_16x16x32_bf16 v[6:9], v[178:181], v[234:237], v[6:9]
	v_mfma_f32_16x16x32_bf16 v[2:5], v[186:189], v[234:237], v[2:5]
	s_barrier
	s_setprio 0
	s_add_i32 s62, 0, 0x18000
	v_add_u32_e32 v143, s62, v140
	s_add_i32 s63, 0, 0x1c000
	ds_read_b128 v[144:147], v143
	ds_read_b128 v[148:151], v143 offset:1024
	ds_read_b128 v[152:155], v143 offset:2048
	ds_read_b128 v[156:159], v143 offset:3072
	v_add_u32_e32 v143, s63, v140
	ds_read_b128 v[160:163], v143
	ds_read_b128 v[178:181], v143 offset:1024
	ds_read_b128 v[182:185], v143 offset:2048
	ds_read_b128 v[186:189], v143 offset:3072
	s_add_u32 s46, s68, 0x80000
	s_addc_u32 s47, s69, 0
	s_mov_b32 m0, s74
	v_lshl_add_u64 v[248:249], s[46:47], 0, v[134:135]
	ds_read_b128 v[206:209], v142 offset:32768
	ds_read_b128 v[210:213], v142 offset:33792
	ds_read_b128 v[214:217], v142 offset:34816
	ds_read_b128 v[218:221], v142 offset:35840
	ds_read_b128 v[222:225], v142 offset:36864
	ds_read_b128 v[226:229], v142 offset:37888
	ds_read_b128 v[230:233], v142 offset:38912
	ds_read_b128 v[234:237], v142 offset:39936
	global_load_lds_dwordx4 v[248:249], off
	v_lshl_add_u64 v[248:249], s[46:47], 0, v[132:133]
	s_mov_b32 m0, s75
	s_nop 0
	global_load_lds_dwordx4 v[248:249], off
	s_waitcnt vmcnt(8)
	s_waitcnt lgkmcnt(0)
	s_setprio 1
	s_waitcnt lgkmcnt(0)
	v_mfma_f32_16x16x32_bf16 v[126:129], v[144:147], v[206:209], v[126:129]
	v_mfma_f32_16x16x32_bf16 v[122:125], v[152:155], v[206:209], v[122:125]
	v_mfma_f32_16x16x32_bf16 v[118:121], v[144:147], v[214:217], v[118:121]
	v_mfma_f32_16x16x32_bf16 v[114:117], v[152:155], v[214:217], v[114:117]
	s_barrier
	v_mfma_f32_16x16x32_bf16 v[102:105], v[144:147], v[222:225], v[102:105]
	v_mfma_f32_16x16x32_bf16 v[98:101], v[152:155], v[222:225], v[98:101]
	v_mfma_f32_16x16x32_bf16 v[86:89], v[144:147], v[230:233], v[86:89]
	v_mfma_f32_16x16x32_bf16 v[82:85], v[152:155], v[230:233], v[82:85]
	v_mfma_f32_16x16x32_bf16 v[126:129], v[148:151], v[210:213], v[126:129]
	v_mfma_f32_16x16x32_bf16 v[122:125], v[156:159], v[210:213], v[122:125]
	v_mfma_f32_16x16x32_bf16 v[118:121], v[148:151], v[218:221], v[118:121]
	v_mfma_f32_16x16x32_bf16 v[114:117], v[156:159], v[218:221], v[114:117]
	v_mfma_f32_16x16x32_bf16 v[102:105], v[148:151], v[226:229], v[102:105]
	v_mfma_f32_16x16x32_bf16 v[98:101], v[156:159], v[226:229], v[98:101]
	v_mfma_f32_16x16x32_bf16 v[86:89], v[148:151], v[234:237], v[86:89]
	v_mfma_f32_16x16x32_bf16 v[82:85], v[156:159], v[234:237], v[82:85]
	v_mfma_f32_16x16x32_bf16 v[110:113], v[160:163], v[206:209], v[110:113]
	v_mfma_f32_16x16x32_bf16 v[106:109], v[182:185], v[206:209], v[106:109]
	v_mfma_f32_16x16x32_bf16 v[94:97], v[160:163], v[214:217], v[94:97]
	v_mfma_f32_16x16x32_bf16 v[90:93], v[182:185], v[214:217], v[90:93]
	v_mfma_f32_16x16x32_bf16 v[78:81], v[160:163], v[222:225], v[78:81]
	v_mfma_f32_16x16x32_bf16 v[74:77], v[182:185], v[222:225], v[74:77]
	v_mfma_f32_16x16x32_bf16 v[70:73], v[160:163], v[230:233], v[70:73]
	v_mfma_f32_16x16x32_bf16 v[66:69], v[182:185], v[230:233], v[66:69]
	v_mfma_f32_16x16x32_bf16 v[110:113], v[178:181], v[210:213], v[110:113]
	v_mfma_f32_16x16x32_bf16 v[106:109], v[186:189], v[210:213], v[106:109]
	v_mfma_f32_16x16x32_bf16 v[94:97], v[178:181], v[218:221], v[94:97]
	v_mfma_f32_16x16x32_bf16 v[90:93], v[186:189], v[218:221], v[90:93]
	v_mfma_f32_16x16x32_bf16 v[78:81], v[178:181], v[226:229], v[78:81]
	v_mfma_f32_16x16x32_bf16 v[74:77], v[186:189], v[226:229], v[74:77]
	v_mfma_f32_16x16x32_bf16 v[70:73], v[178:181], v[234:237], v[70:73]
	v_mfma_f32_16x16x32_bf16 v[66:69], v[186:189], v[234:237], v[66:69]
	s_barrier
	s_setprio 0
	s_add_i32 s46, s62, s71
	v_lshl_add_u64 v[164:165], v[164:165], 0, s[42:43]
	s_mov_b32 m0, s46
	ds_read_b128 v[206:209], v142 offset:49152
	ds_read_b128 v[210:213], v142 offset:50176
	ds_read_b128 v[214:217], v142 offset:51200
	ds_read_b128 v[218:221], v142 offset:52224
	ds_read_b128 v[222:225], v142 offset:53248
	ds_read_b128 v[226:229], v142 offset:54272
	ds_read_b128 v[230:233], v142 offset:55296
	ds_read_b128 v[234:237], v142 offset:56320
	global_load_lds_dwordx4 v[164:165], off
	s_add_i32 m0, s46, 0x2000
	s_add_u32 s46, s60, 0x80080
	v_lshl_add_u64 v[164:165], v[242:243], 0, s[42:43]
	s_addc_u32 s47, s61, 0
	s_add_i32 s60, s63, s71
	global_load_lds_dwordx4 v[164:165], off
	v_lshl_add_u64 v[164:165], s[46:47], 0, v[166:167]
	s_mov_b32 m0, s60
	s_nop 0
	global_load_lds_dwordx4 v[164:165], off
	v_lshl_add_u64 v[164:165], s[46:47], 0, v[130:131]
	s_add_i32 m0, s60, 0x2000
	s_nop 0
	global_load_lds_dwordx4 v[164:165], off
	v_lshl_add_u64 v[164:165], v[244:245], 0, s[42:43]
	s_mov_b32 m0, s76
	s_nop 0
	global_load_lds_dwordx4 v[164:165], off
	v_lshl_add_u64 v[164:165], v[246:247], 0, s[42:43]
	s_mov_b32 m0, s77
	s_nop 0
	global_load_lds_dwordx4 v[164:165], off
	s_waitcnt vmcnt(8)
	s_waitcnt lgkmcnt(0)
	s_setprio 1
	s_waitcnt lgkmcnt(0)
	v_mfma_f32_16x16x32_bf16 v[62:65], v[144:147], v[206:209], v[62:65]
	v_mfma_f32_16x16x32_bf16 v[58:61], v[152:155], v[206:209], v[58:61]
	v_mfma_f32_16x16x32_bf16 v[54:57], v[144:147], v[214:217], v[54:57]
	v_mfma_f32_16x16x32_bf16 v[50:53], v[152:155], v[214:217], v[50:53]
	s_barrier
	v_mfma_f32_16x16x32_bf16 v[38:41], v[144:147], v[222:225], v[38:41]
	v_mfma_f32_16x16x32_bf16 v[34:37], v[152:155], v[222:225], v[34:37]
	v_mfma_f32_16x16x32_bf16 v[22:25], v[144:147], v[230:233], v[22:25]
	v_mfma_f32_16x16x32_bf16 v[18:21], v[152:155], v[230:233], v[18:21]
	v_mfma_f32_16x16x32_bf16 v[62:65], v[148:151], v[210:213], v[62:65]
	v_mfma_f32_16x16x32_bf16 v[58:61], v[156:159], v[210:213], v[58:61]
	v_mfma_f32_16x16x32_bf16 v[54:57], v[148:151], v[218:221], v[54:57]
	v_mfma_f32_16x16x32_bf16 v[50:53], v[156:159], v[218:221], v[50:53]
	v_mfma_f32_16x16x32_bf16 v[38:41], v[148:151], v[226:229], v[38:41]
	v_mfma_f32_16x16x32_bf16 v[34:37], v[156:159], v[226:229], v[34:37]
	v_mfma_f32_16x16x32_bf16 v[22:25], v[148:151], v[234:237], v[22:25]
	v_mfma_f32_16x16x32_bf16 v[18:21], v[156:159], v[234:237], v[18:21]
	v_mfma_f32_16x16x32_bf16 v[46:49], v[160:163], v[206:209], v[46:49]
	v_mfma_f32_16x16x32_bf16 v[42:45], v[182:185], v[206:209], v[42:45]
	v_mfma_f32_16x16x32_bf16 v[30:33], v[160:163], v[214:217], v[30:33]
	v_mfma_f32_16x16x32_bf16 v[26:29], v[182:185], v[214:217], v[26:29]
	v_mfma_f32_16x16x32_bf16 v[14:17], v[160:163], v[222:225], v[14:17]
	v_mfma_f32_16x16x32_bf16 v[10:13], v[182:185], v[222:225], v[10:13]
	v_mfma_f32_16x16x32_bf16 v[6:9], v[160:163], v[230:233], v[6:9]
	v_mfma_f32_16x16x32_bf16 v[2:5], v[182:185], v[230:233], v[2:5]
	v_mfma_f32_16x16x32_bf16 v[46:49], v[178:181], v[210:213], v[46:49]
	v_mfma_f32_16x16x32_bf16 v[42:45], v[186:189], v[210:213], v[42:45]
	v_mfma_f32_16x16x32_bf16 v[30:33], v[178:181], v[218:221], v[30:33]
	v_mfma_f32_16x16x32_bf16 v[26:29], v[186:189], v[218:221], v[26:29]
	v_mfma_f32_16x16x32_bf16 v[14:17], v[178:181], v[226:229], v[14:17]
	v_mfma_f32_16x16x32_bf16 v[10:13], v[186:189], v[226:229], v[10:13]
	v_mfma_f32_16x16x32_bf16 v[6:9], v[178:181], v[234:237], v[6:9]
	v_mfma_f32_16x16x32_bf16 v[2:5], v[186:189], v[234:237], v[2:5]
	s_barrier
	s_setprio 0
	s_add_i32 s82, s82, 2
	s_add_u32 s66, s66, 0x100
	s_addc_u32 s67, s67, 0
	s_add_u32 s80, s80, 0x100
	s_addc_u32 s81, s81, 0
	s_cmp_gt_u32 s82, 29
	s_cbranch_scc0 .LBB0_168
	s_and_b64 vcc, exec, s[10:11]
	s_cbranch_vccz .LBB0_171
	s_barrier

.LBB0_426:
	s_add_u32 s46, s66, 0xfffe0080
	s_addc_u32 s47, s67, -1
	s_add_i32 s62, 0, 0x10000
	s_cmp_eq_u32 s84, 4
	s_cselect_b32 s69, s19, s47
	s_cselect_b32 s68, s80, s46
	v_add_u32_e32 v143, s62, v140
	s_cselect_b32 s61, s17, s83
	s_cselect_b32 s60, s81, s82
	s_add_i32 s63, 0, 0x14000
	ds_read_b128 v[144:147], v143
	ds_read_b128 v[148:151], v143 offset:1024
	ds_read_b128 v[152:155], v143 offset:2048
	ds_read_b128 v[156:159], v143 offset:3072
	v_add_u32_e32 v143, s63, v140
	ds_read_b128 v[160:163], v143
	ds_read_b128 v[178:181], v143 offset:1024
	ds_read_b128 v[182:185], v143 offset:2048
	ds_read_b128 v[186:189], v143 offset:3072
	v_lshl_add_u64 v[164:165], s[66:67], 0, v[136:137]
	s_add_i32 m0, s11, 0xc000
	ds_read_b128 v[206:209], v142
	ds_read_b128 v[210:213], v142 offset:1024
	ds_read_b128 v[214:217], v142 offset:2048
	ds_read_b128 v[218:221], v142 offset:3072
	ds_read_b128 v[222:225], v142 offset:4096
	ds_read_b128 v[226:229], v142 offset:5120
	ds_read_b128 v[230:233], v142 offset:6144
	ds_read_b128 v[234:237], v142 offset:7168
	global_load_lds_dwordx4 v[164:165], off
	v_lshl_add_u64 v[164:165], s[66:67], 0, v[138:139]
	s_add_i32 m0, s11, 0xe000
	s_nop 0
	global_load_lds_dwordx4 v[164:165], off
	s_waitcnt vmcnt(8)
	s_waitcnt lgkmcnt(0)
	s_setprio 1
	s_waitcnt lgkmcnt(0)
	v_mfma_f32_16x16x32_bf16 v[126:129], v[144:147], v[206:209], v[126:129]
	v_mfma_f32_16x16x32_bf16 v[122:125], v[152:155], v[206:209], v[122:125]
	v_mfma_f32_16x16x32_bf16 v[118:121], v[144:147], v[214:217], v[118:121]
	v_mfma_f32_16x16x32_bf16 v[114:117], v[152:155], v[214:217], v[114:117]
	s_barrier
	v_mfma_f32_16x16x32_bf16 v[102:105], v[144:147], v[222:225], v[102:105]
	v_mfma_f32_16x16x32_bf16 v[98:101], v[152:155], v[222:225], v[98:101]
	v_mfma_f32_16x16x32_bf16 v[86:89], v[144:147], v[230:233], v[86:89]
	v_mfma_f32_16x16x32_bf16 v[82:85], v[152:155], v[230:233], v[82:85]
	v_mfma_f32_16x16x32_bf16 v[126:129], v[148:151], v[210:213], v[126:129]
	v_mfma_f32_16x16x32_bf16 v[122:125], v[156:159], v[210:213], v[122:125]
	v_mfma_f32_16x16x32_bf16 v[118:121], v[148:151], v[218:221], v[118:121]
	v_mfma_f32_16x16x32_bf16 v[114:117], v[156:159], v[218:221], v[114:117]
	v_mfma_f32_16x16x32_bf16 v[102:105], v[148:151], v[226:229], v[102:105]
	v_mfma_f32_16x16x32_bf16 v[98:101], v[156:159], v[226:229], v[98:101]
	v_mfma_f32_16x16x32_bf16 v[86:89], v[148:151], v[234:237], v[86:89]
	v_mfma_f32_16x16x32_bf16 v[82:85], v[156:159], v[234:237], v[82:85]
	v_mfma_f32_16x16x32_bf16 v[110:113], v[160:163], v[206:209], v[110:113]
	v_mfma_f32_16x16x32_bf16 v[106:109], v[182:185], v[206:209], v[106:109]
	v_mfma_f32_16x16x32_bf16 v[94:97], v[160:163], v[214:217], v[94:97]
	v_mfma_f32_16x16x32_bf16 v[90:93], v[182:185], v[214:217], v[90:93]
	v_mfma_f32_16x16x32_bf16 v[78:81], v[160:163], v[222:225], v[78:81]
	v_mfma_f32_16x16x32_bf16 v[74:77], v[182:185], v[222:225], v[74:77]
	v_mfma_f32_16x16x32_bf16 v[70:73], v[160:163], v[230:233], v[70:73]
	v_mfma_f32_16x16x32_bf16 v[66:69], v[182:185], v[230:233], v[66:69]
	v_mfma_f32_16x16x32_bf16 v[110:113], v[178:181], v[210:213], v[110:113]
	v_mfma_f32_16x16x32_bf16 v[106:109], v[186:189], v[210:213], v[106:109]
	v_mfma_f32_16x16x32_bf16 v[94:97], v[178:181], v[218:221], v[94:97]
	v_mfma_f32_16x16x32_bf16 v[90:93], v[186:189], v[218:221], v[90:93]
	v_mfma_f32_16x16x32_bf16 v[78:81], v[178:181], v[226:229], v[78:81]
	v_mfma_f32_16x16x32_bf16 v[74:77], v[186:189], v[226:229], v[74:77]
	v_mfma_f32_16x16x32_bf16 v[70:73], v[178:181], v[234:237], v[70:73]
	v_mfma_f32_16x16x32_bf16 v[66:69], v[186:189], v[234:237], v[66:69]
	s_barrier
	s_setprio 0
	s_add_i32 s46, s62, s72
	v_lshl_add_u64 v[164:165], s[60:61], 0, v[166:167]
	s_mov_b32 m0, s46
	ds_read_b128 v[206:209], v142 offset:16384
	ds_read_b128 v[210:213], v142 offset:17408
	ds_read_b128 v[214:217], v142 offset:18432
	ds_read_b128 v[218:221], v142 offset:19456
	ds_read_b128 v[222:225], v142 offset:20480
	ds_read_b128 v[226:229], v142 offset:21504
	ds_read_b128 v[230:233], v142 offset:22528
	ds_read_b128 v[234:237], v142 offset:23552
	global_load_lds_dwordx4 v[164:165], off
	s_add_i32 m0, s46, 0x2000
	s_add_u32 s46, s60, 0x20000
	v_lshl_add_u64 v[242:243], s[60:61], 0, v[130:131]
	s_addc_u32 s47, s61, 0
	s_add_i32 s62, s63, s72
	global_load_lds_dwordx4 v[242:243], off
	v_lshl_add_u64 v[244:245], s[46:47], 0, v[166:167]
	s_mov_b32 m0, s62
	v_lshl_add_u64 v[246:247], s[68:69], 0, v[132:133]
	global_load_lds_dwordx4 v[244:245], off
	v_lshl_add_u64 v[244:245], s[46:47], 0, v[130:131]
	s_add_i32 m0, s62, 0x2000
	s_nop 0
	global_load_lds_dwordx4 v[244:245], off
	v_lshl_add_u64 v[244:245], s[68:69], 0, v[134:135]
	s_mov_b32 m0, s11
	s_nop 0
	global_load_lds_dwordx4 v[244:245], off
	s_mov_b32 m0, s74
	s_nop 0
	global_load_lds_dwordx4 v[246:247], off
	s_waitcnt vmcnt(8)
	s_waitcnt lgkmcnt(0)
	s_setprio 1
	s_waitcnt lgkmcnt(0)
	v_mfma_f32_16x16x32_bf16 v[62:65], v[144:147], v[206:209], v[62:65]
	v_mfma_f32_16x16x32_bf16 v[58:61], v[152:155], v[206:209], v[58:61]
	v_mfma_f32_16x16x32_bf16 v[54:57], v[144:147], v[214:217], v[54:57]
	v_mfma_f32_16x16x32_bf16 v[50:53], v[152:155], v[214:217], v[50:53]
	s_barrier
	v_mfma_f32_16x16x32_bf16 v[38:41], v[144:147], v[222:225], v[38:41]
	v_mfma_f32_16x16x32_bf16 v[34:37], v[152:155], v[222:225], v[34:37]
	v_mfma_f32_16x16x32_bf16 v[22:25], v[144:147], v[230:233], v[22:25]
	v_mfma_f32_16x16x32_bf16 v[18:21], v[152:155], v[230:233], v[18:21]
	v_mfma_f32_16x16x32_bf16 v[62:65], v[148:151], v[210:213], v[62:65]
	v_mfma_f32_16x16x32_bf16 v[58:61], v[156:159], v[210:213], v[58:61]
	v_mfma_f32_16x16x32_bf16 v[54:57], v[148:151], v[218:221], v[54:57]
	v_mfma_f32_16x16x32_bf16 v[50:53], v[156:159], v[218:221], v[50:53]
	v_mfma_f32_16x16x32_bf16 v[38:41], v[148:151], v[226:229], v[38:41]
	v_mfma_f32_16x16x32_bf16 v[34:37], v[156:159], v[226:229], v[34:37]
	v_mfma_f32_16x16x32_bf16 v[22:25], v[148:151], v[234:237], v[22:25]
	v_mfma_f32_16x16x32_bf16 v[18:21], v[156:159], v[234:237], v[18:21]
	v_mfma_f32_16x16x32_bf16 v[46:49], v[160:163], v[206:209], v[46:49]
	v_mfma_f32_16x16x32_bf16 v[42:45], v[182:185], v[206:209], v[42:45]
	v_mfma_f32_16x16x32_bf16 v[30:33], v[160:163], v[214:217], v[30:33]
	v_mfma_f32_16x16x32_bf16 v[26:29], v[182:185], v[214:217], v[26:29]
	v_mfma_f32_16x16x32_bf16 v[14:17], v[160:163], v[222:225], v[14:17]
	v_mfma_f32_16x16x32_bf16 v[10:13], v[182:185], v[222:225], v[10:13]
	v_mfma_f32_16x16x32_bf16 v[6:9], v[160:163], v[230:233], v[6:9]
	v_mfma_f32_16x16x32_bf16 v[2:5], v[182:185], v[230:233], v[2:5]
	v_mfma_f32_16x16x32_bf16 v[46:49], v[178:181], v[210:213], v[46:49]
	v_mfma_f32_16x16x32_bf16 v[42:45], v[186:189], v[210:213], v[42:45]
	v_mfma_f32_16x16x32_bf16 v[30:33], v[178:181], v[218:221], v[30:33]
	v_mfma_f32_16x16x32_bf16 v[26:29], v[186:189], v[218:221], v[26:29]
	v_mfma_f32_16x16x32_bf16 v[14:17], v[178:181], v[226:229], v[14:17]
	v_mfma_f32_16x16x32_bf16 v[10:13], v[186:189], v[226:229], v[10:13]
	v_mfma_f32_16x16x32_bf16 v[6:9], v[178:181], v[234:237], v[6:9]
	v_mfma_f32_16x16x32_bf16 v[2:5], v[186:189], v[234:237], v[2:5]
	s_barrier
	s_setprio 0
	s_add_i32 s62, 0, 0x18000
	v_add_u32_e32 v143, s62, v140
	s_add_i32 s63, 0, 0x1c000
	ds_read_b128 v[144:147], v143
	ds_read_b128 v[148:151], v143 offset:1024
	ds_read_b128 v[152:155], v143 offset:2048
	ds_read_b128 v[156:159], v143 offset:3072
	v_add_u32_e32 v143, s63, v140
	ds_read_b128 v[160:163], v143
	ds_read_b128 v[178:181], v143 offset:1024
	ds_read_b128 v[182:185], v143 offset:2048
	ds_read_b128 v[186:189], v143 offset:3072
	s_add_u32 s46, s68, 0x20000
	s_addc_u32 s47, s69, 0
	s_mov_b32 m0, s75
	v_lshl_add_u64 v[248:249], s[46:47], 0, v[134:135]
	ds_read_b128 v[206:209], v142 offset:32768
	ds_read_b128 v[210:213], v142 offset:33792
	ds_read_b128 v[214:217], v142 offset:34816
	ds_read_b128 v[218:221], v142 offset:35840
	ds_read_b128 v[222:225], v142 offset:36864
	ds_read_b128 v[226:229], v142 offset:37888
	ds_read_b128 v[230:233], v142 offset:38912
	ds_read_b128 v[234:237], v142 offset:39936
	global_load_lds_dwordx4 v[248:249], off
	v_lshl_add_u64 v[248:249], s[46:47], 0, v[132:133]
	s_mov_b32 m0, s76
	s_nop 0
	global_load_lds_dwordx4 v[248:249], off
	s_waitcnt vmcnt(8)
	s_waitcnt lgkmcnt(0)
	s_setprio 1
	s_waitcnt lgkmcnt(0)
	v_mfma_f32_16x16x32_bf16 v[126:129], v[144:147], v[206:209], v[126:129]
	v_mfma_f32_16x16x32_bf16 v[122:125], v[152:155], v[206:209], v[122:125]
	v_mfma_f32_16x16x32_bf16 v[118:121], v[144:147], v[214:217], v[118:121]
	v_mfma_f32_16x16x32_bf16 v[114:117], v[152:155], v[214:217], v[114:117]
	s_barrier
	v_mfma_f32_16x16x32_bf16 v[102:105], v[144:147], v[222:225], v[102:105]
	v_mfma_f32_16x16x32_bf16 v[98:101], v[152:155], v[222:225], v[98:101]
	v_mfma_f32_16x16x32_bf16 v[86:89], v[144:147], v[230:233], v[86:89]
	v_mfma_f32_16x16x32_bf16 v[82:85], v[152:155], v[230:233], v[82:85]
	v_mfma_f32_16x16x32_bf16 v[126:129], v[148:151], v[210:213], v[126:129]
	v_mfma_f32_16x16x32_bf16 v[122:125], v[156:159], v[210:213], v[122:125]
	v_mfma_f32_16x16x32_bf16 v[118:121], v[148:151], v[218:221], v[118:121]
	v_mfma_f32_16x16x32_bf16 v[114:117], v[156:159], v[218:221], v[114:117]
	v_mfma_f32_16x16x32_bf16 v[102:105], v[148:151], v[226:229], v[102:105]
	v_mfma_f32_16x16x32_bf16 v[98:101], v[156:159], v[226:229], v[98:101]
	v_mfma_f32_16x16x32_bf16 v[86:89], v[148:151], v[234:237], v[86:89]
	v_mfma_f32_16x16x32_bf16 v[82:85], v[156:159], v[234:237], v[82:85]
	v_mfma_f32_16x16x32_bf16 v[110:113], v[160:163], v[206:209], v[110:113]
	v_mfma_f32_16x16x32_bf16 v[106:109], v[182:185], v[206:209], v[106:109]
	v_mfma_f32_16x16x32_bf16 v[94:97], v[160:163], v[214:217], v[94:97]
	v_mfma_f32_16x16x32_bf16 v[90:93], v[182:185], v[214:217], v[90:93]
	v_mfma_f32_16x16x32_bf16 v[78:81], v[160:163], v[222:225], v[78:81]
	v_mfma_f32_16x16x32_bf16 v[74:77], v[182:185], v[222:225], v[74:77]
	v_mfma_f32_16x16x32_bf16 v[70:73], v[160:163], v[230:233], v[70:73]
	v_mfma_f32_16x16x32_bf16 v[66:69], v[182:185], v[230:233], v[66:69]
	v_mfma_f32_16x16x32_bf16 v[110:113], v[178:181], v[210:213], v[110:113]
	v_mfma_f32_16x16x32_bf16 v[106:109], v[186:189], v[210:213], v[106:109]
	v_mfma_f32_16x16x32_bf16 v[94:97], v[178:181], v[218:221], v[94:97]
	v_mfma_f32_16x16x32_bf16 v[90:93], v[186:189], v[218:221], v[90:93]
	v_mfma_f32_16x16x32_bf16 v[78:81], v[178:181], v[226:229], v[78:81]
	v_mfma_f32_16x16x32_bf16 v[74:77], v[186:189], v[226:229], v[74:77]
	v_mfma_f32_16x16x32_bf16 v[70:73], v[178:181], v[234:237], v[70:73]
	v_mfma_f32_16x16x32_bf16 v[66:69], v[186:189], v[234:237], v[66:69]
	s_barrier
	s_setprio 0
	s_add_i32 s46, s62, s72
	v_lshl_add_u64 v[164:165], v[164:165], 0, s[42:43]
	s_mov_b32 m0, s46
	ds_read_b128 v[206:209], v142 offset:49152
	ds_read_b128 v[210:213], v142 offset:50176
	ds_read_b128 v[214:217], v142 offset:51200
	ds_read_b128 v[218:221], v142 offset:52224
	ds_read_b128 v[222:225], v142 offset:53248
	ds_read_b128 v[226:229], v142 offset:54272
	ds_read_b128 v[230:233], v142 offset:55296
	ds_read_b128 v[234:237], v142 offset:56320
	global_load_lds_dwordx4 v[164:165], off
	s_add_i32 m0, s46, 0x2000
	s_add_u32 s46, s60, 0x20080
	v_lshl_add_u64 v[164:165], v[242:243], 0, s[42:43]
	s_addc_u32 s47, s61, 0
	s_add_i32 s60, s63, s72
	global_load_lds_dwordx4 v[164:165], off
	v_lshl_add_u64 v[164:165], s[46:47], 0, v[166:167]
	s_mov_b32 m0, s60
	s_nop 0
	global_load_lds_dwordx4 v[164:165], off
	v_lshl_add_u64 v[164:165], s[46:47], 0, v[130:131]
	s_add_i32 m0, s60, 0x2000
	s_nop 0
	global_load_lds_dwordx4 v[164:165], off
	v_lshl_add_u64 v[164:165], v[244:245], 0, s[42:43]
	s_mov_b32 m0, s77
	s_nop 0
	global_load_lds_dwordx4 v[164:165], off
	v_lshl_add_u64 v[164:165], v[246:247], 0, s[42:43]
	s_mov_b32 m0, s78
	s_nop 0
	global_load_lds_dwordx4 v[164:165], off
	s_waitcnt vmcnt(8)
	s_waitcnt lgkmcnt(0)
	s_setprio 1
	s_waitcnt lgkmcnt(0)
	v_mfma_f32_16x16x32_bf16 v[62:65], v[144:147], v[206:209], v[62:65]
	v_mfma_f32_16x16x32_bf16 v[58:61], v[152:155], v[206:209], v[58:61]
	v_mfma_f32_16x16x32_bf16 v[54:57], v[144:147], v[214:217], v[54:57]
	v_mfma_f32_16x16x32_bf16 v[50:53], v[152:155], v[214:217], v[50:53]
	s_barrier
	v_mfma_f32_16x16x32_bf16 v[38:41], v[144:147], v[222:225], v[38:41]
	v_mfma_f32_16x16x32_bf16 v[34:37], v[152:155], v[222:225], v[34:37]
	v_mfma_f32_16x16x32_bf16 v[22:25], v[144:147], v[230:233], v[22:25]
	v_mfma_f32_16x16x32_bf16 v[18:21], v[152:155], v[230:233], v[18:21]
	v_mfma_f32_16x16x32_bf16 v[62:65], v[148:151], v[210:213], v[62:65]
	v_mfma_f32_16x16x32_bf16 v[58:61], v[156:159], v[210:213], v[58:61]
	v_mfma_f32_16x16x32_bf16 v[54:57], v[148:151], v[218:221], v[54:57]
	v_mfma_f32_16x16x32_bf16 v[50:53], v[156:159], v[218:221], v[50:53]
	v_mfma_f32_16x16x32_bf16 v[38:41], v[148:151], v[226:229], v[38:41]
	v_mfma_f32_16x16x32_bf16 v[34:37], v[156:159], v[226:229], v[34:37]
	v_mfma_f32_16x16x32_bf16 v[22:25], v[148:151], v[234:237], v[22:25]
	v_mfma_f32_16x16x32_bf16 v[18:21], v[156:159], v[234:237], v[18:21]
	v_mfma_f32_16x16x32_bf16 v[46:49], v[160:163], v[206:209], v[46:49]
	v_mfma_f32_16x16x32_bf16 v[42:45], v[182:185], v[206:209], v[42:45]
	v_mfma_f32_16x16x32_bf16 v[30:33], v[160:163], v[214:217], v[30:33]
	v_mfma_f32_16x16x32_bf16 v[26:29], v[182:185], v[214:217], v[26:29]
	v_mfma_f32_16x16x32_bf16 v[14:17], v[160:163], v[222:225], v[14:17]
	v_mfma_f32_16x16x32_bf16 v[10:13], v[182:185], v[222:225], v[10:13]
	v_mfma_f32_16x16x32_bf16 v[6:9], v[160:163], v[230:233], v[6:9]
	v_mfma_f32_16x16x32_bf16 v[2:5], v[182:185], v[230:233], v[2:5]
	v_mfma_f32_16x16x32_bf16 v[46:49], v[178:181], v[210:213], v[46:49]
	v_mfma_f32_16x16x32_bf16 v[42:45], v[186:189], v[210:213], v[42:45]
	v_mfma_f32_16x16x32_bf16 v[30:33], v[178:181], v[218:221], v[30:33]
	v_mfma_f32_16x16x32_bf16 v[26:29], v[186:189], v[218:221], v[26:29]
	v_mfma_f32_16x16x32_bf16 v[14:17], v[178:181], v[226:229], v[14:17]
	v_mfma_f32_16x16x32_bf16 v[10:13], v[186:189], v[226:229], v[10:13]
	v_mfma_f32_16x16x32_bf16 v[6:9], v[178:181], v[234:237], v[6:9]
	v_mfma_f32_16x16x32_bf16 v[2:5], v[186:189], v[234:237], v[2:5]
	s_barrier
	s_setprio 0
	s_add_i32 s84, s84, 2
	s_add_u32 s66, s66, 0x100
	s_addc_u32 s67, s67, 0
	s_add_u32 s82, s82, 0x100
	s_addc_u32 s83, s83, 0
	s_cmp_gt_u32 s84, 5
	s_cbranch_scc0 .LBB0_426
	s_and_b64 vcc, exec, s[12:13]
	s_cbranch_vccz .LBB0_429
	s_barrier

.LBB0_442:
	s_add_u32 s62, s18, s72
	s_addc_u32 s63, s19, 0
	s_add_u32 s73, s62, 0x100
	s_addc_u32 s74, s63, 0
	s_and_b64 s[46:47], s[60:61], exec
	s_cselect_b32 s75, s23, s74
	s_cselect_b32 s74, s92, s73
	s_add_u32 s46, s16, s72
	s_addc_u32 s47, s17, 0
	s_add_u32 s72, s46, 0x100
	s_addc_u32 s73, s47, 0
	s_add_i32 s48, 0, 0x10000
	s_and_b64 s[46:47], s[60:61], exec
	s_cselect_b32 s77, s21, s73
	s_cselect_b32 s76, s93, s72
	s_add_i32 s46, 0, 0x14000
	s_add_u32 s80, s62, 0x10080
	s_addc_u32 s81, s63, 0
	s_add_i32 s63, s48, s84
	s_add_i32 m0, s13, 0xc000
	s_add_i32 s49, s13, 0xe000
	s_add_i32 vcc_lo, s63, 0x2000
	v_add_u32_e32 v139, s48, v136
	s_add_u32 s78, s76, 0x10000
	ds_read_b128 v[140:143], v139
	ds_read_b128 v[144:147], v139 offset:1024
	ds_read_b128 v[148:151], v139 offset:2048
	ds_read_b128 v[152:155], v139 offset:3072
	v_add_u32_e32 v139, s46, v136
	s_addc_u32 s79, s77, 0
	s_add_i32 vcc_hi, s46, s84
	ds_read_b128 v[156:159], v139
	ds_read_b128 v[160:163], v139 offset:1024
	ds_read_b128 v[178:181], v139 offset:2048
	ds_read_b128 v[182:185], v139 offset:3072
	s_add_i32 s62, vcc_hi, 0x2000
	s_add_i32 s97, 0, 0x18000
	s_add_i32 s96, 0, 0x1c000
	s_add_u32 s72, s74, 0x10000
	s_addc_u32 s73, s75, 0
	s_add_i32 s95, s97, s84
	s_add_i32 s94, s95, 0x2000
	s_add_u32 s60, s76, 0x10080
	s_addc_u32 s61, s77, 0
	s_add_i32 s47, s96, s84
	s_add_i32 s46, s47, 0x2000
	v_lshl_add_u64 v[164:165], s[80:81], 0, v[134:135]
	ds_read_b128 v[186:189], v138
	ds_read_b128 v[206:209], v138 offset:1024
	ds_read_b128 v[210:213], v138 offset:2048
	ds_read_b128 v[214:217], v138 offset:3072
	ds_read_b128 v[218:221], v138 offset:4096
	ds_read_b128 v[222:225], v138 offset:5120
	ds_read_b128 v[226:229], v138 offset:6144
	ds_read_b128 v[230:233], v138 offset:7168
	global_load_lds_dwordx4 v[164:165], off
	v_lshl_add_u64 v[164:165], s[80:81], 0, v[132:133]
	s_mov_b32 m0, s49
	s_nop 0
	global_load_lds_dwordx4 v[164:165], off
	s_waitcnt vmcnt(8)
	s_waitcnt lgkmcnt(0)
	s_setprio 1
	s_waitcnt lgkmcnt(0)
	v_mfma_f32_16x16x32_bf16 v[126:129], v[140:143], v[186:189], v[126:129]
	v_mfma_f32_16x16x32_bf16 v[122:125], v[148:151], v[186:189], v[122:125]
	v_mfma_f32_16x16x32_bf16 v[118:121], v[140:143], v[210:213], v[118:121]
	v_mfma_f32_16x16x32_bf16 v[114:117], v[148:151], v[210:213], v[114:117]
	s_barrier
	v_mfma_f32_16x16x32_bf16 v[102:105], v[140:143], v[218:221], v[102:105]
	v_mfma_f32_16x16x32_bf16 v[98:101], v[148:151], v[218:221], v[98:101]
	v_mfma_f32_16x16x32_bf16 v[86:89], v[140:143], v[226:229], v[86:89]
	v_mfma_f32_16x16x32_bf16 v[82:85], v[148:151], v[226:229], v[82:85]
	v_mfma_f32_16x16x32_bf16 v[126:129], v[144:147], v[206:209], v[126:129]
	v_mfma_f32_16x16x32_bf16 v[122:125], v[152:155], v[206:209], v[122:125]
	v_mfma_f32_16x16x32_bf16 v[118:121], v[144:147], v[214:217], v[118:121]
	v_mfma_f32_16x16x32_bf16 v[114:117], v[152:155], v[214:217], v[114:117]
	v_mfma_f32_16x16x32_bf16 v[102:105], v[144:147], v[222:225], v[102:105]
	v_mfma_f32_16x16x32_bf16 v[98:101], v[152:155], v[222:225], v[98:101]
	v_mfma_f32_16x16x32_bf16 v[86:89], v[144:147], v[230:233], v[86:89]
	v_mfma_f32_16x16x32_bf16 v[82:85], v[152:155], v[230:233], v[82:85]
	v_mfma_f32_16x16x32_bf16 v[110:113], v[156:159], v[186:189], v[110:113]
	v_mfma_f32_16x16x32_bf16 v[106:109], v[178:181], v[186:189], v[106:109]
	v_mfma_f32_16x16x32_bf16 v[94:97], v[156:159], v[210:213], v[94:97]
	v_mfma_f32_16x16x32_bf16 v[90:93], v[178:181], v[210:213], v[90:93]
	v_mfma_f32_16x16x32_bf16 v[78:81], v[156:159], v[218:221], v[78:81]
	v_mfma_f32_16x16x32_bf16 v[74:77], v[178:181], v[218:221], v[74:77]
	v_mfma_f32_16x16x32_bf16 v[70:73], v[156:159], v[226:229], v[70:73]
	v_mfma_f32_16x16x32_bf16 v[66:69], v[178:181], v[226:229], v[66:69]
	v_mfma_f32_16x16x32_bf16 v[110:113], v[160:163], v[206:209], v[110:113]
	v_mfma_f32_16x16x32_bf16 v[106:109], v[182:185], v[206:209], v[106:109]
	v_mfma_f32_16x16x32_bf16 v[94:97], v[160:163], v[214:217], v[94:97]
	v_mfma_f32_16x16x32_bf16 v[90:93], v[182:185], v[214:217], v[90:93]
	v_mfma_f32_16x16x32_bf16 v[78:81], v[160:163], v[222:225], v[78:81]
	v_mfma_f32_16x16x32_bf16 v[74:77], v[182:185], v[222:225], v[74:77]
	v_mfma_f32_16x16x32_bf16 v[70:73], v[160:163], v[230:233], v[70:73]
	v_mfma_f32_16x16x32_bf16 v[66:69], v[182:185], v[230:233], v[66:69]
	s_barrier
	s_setprio 0
	s_mov_b32 m0, s63
	v_lshl_add_u64 v[164:165], s[76:77], 0, v[166:167]
	ds_read_b128 v[186:189], v138 offset:16384
	ds_read_b128 v[206:209], v138 offset:17408
	ds_read_b128 v[210:213], v138 offset:18432
	ds_read_b128 v[214:217], v138 offset:19456
	ds_read_b128 v[218:221], v138 offset:20480
	ds_read_b128 v[222:225], v138 offset:21504
	ds_read_b128 v[226:229], v138 offset:22528
	ds_read_b128 v[230:233], v138 offset:23552
	global_load_lds_dwordx4 v[164:165], off
	v_lshl_add_u64 v[234:235], s[76:77], 0, v[130:131]
	s_mov_b32 m0, vcc_lo
	v_lshl_add_u64 v[236:237], s[78:79], 0, v[166:167]
	global_load_lds_dwordx4 v[234:235], off
	s_mov_b32 m0, vcc_hi
	v_lshl_add_u64 v[242:243], s[74:75], 0, v[132:133]
	global_load_lds_dwordx4 v[236:237], off
	v_lshl_add_u64 v[236:237], s[78:79], 0, v[130:131]
	s_mov_b32 m0, s62
	s_nop 0
	global_load_lds_dwordx4 v[236:237], off
	v_lshl_add_u64 v[236:237], s[74:75], 0, v[134:135]
	s_mov_b32 m0, s13
	s_nop 0
	global_load_lds_dwordx4 v[236:237], off
	s_mov_b32 m0, s86
	s_nop 0
	global_load_lds_dwordx4 v[242:243], off
	s_waitcnt vmcnt(8)
	s_waitcnt lgkmcnt(0)
	s_setprio 1
	s_waitcnt lgkmcnt(0)
	v_mfma_f32_16x16x32_bf16 v[62:65], v[140:143], v[186:189], v[62:65]
	v_mfma_f32_16x16x32_bf16 v[58:61], v[148:151], v[186:189], v[58:61]
	v_mfma_f32_16x16x32_bf16 v[54:57], v[140:143], v[210:213], v[54:57]
	v_mfma_f32_16x16x32_bf16 v[50:53], v[148:151], v[210:213], v[50:53]
	s_barrier
	v_mfma_f32_16x16x32_bf16 v[38:41], v[140:143], v[218:221], v[38:41]
	v_mfma_f32_16x16x32_bf16 v[34:37], v[148:151], v[218:221], v[34:37]
	v_mfma_f32_16x16x32_bf16 v[22:25], v[140:143], v[226:229], v[22:25]
	v_mfma_f32_16x16x32_bf16 v[18:21], v[148:151], v[226:229], v[18:21]
	v_mfma_f32_16x16x32_bf16 v[62:65], v[144:147], v[206:209], v[62:65]
	v_mfma_f32_16x16x32_bf16 v[58:61], v[152:155], v[206:209], v[58:61]
	v_mfma_f32_16x16x32_bf16 v[54:57], v[144:147], v[214:217], v[54:57]
	v_mfma_f32_16x16x32_bf16 v[50:53], v[152:155], v[214:217], v[50:53]
	v_mfma_f32_16x16x32_bf16 v[38:41], v[144:147], v[222:225], v[38:41]
	v_mfma_f32_16x16x32_bf16 v[34:37], v[152:155], v[222:225], v[34:37]
	v_mfma_f32_16x16x32_bf16 v[22:25], v[144:147], v[230:233], v[22:25]
	v_mfma_f32_16x16x32_bf16 v[18:21], v[152:155], v[230:233], v[18:21]
	v_mfma_f32_16x16x32_bf16 v[46:49], v[156:159], v[186:189], v[46:49]
	v_mfma_f32_16x16x32_bf16 v[42:45], v[178:181], v[186:189], v[42:45]
	v_mfma_f32_16x16x32_bf16 v[30:33], v[156:159], v[210:213], v[30:33]
	v_mfma_f32_16x16x32_bf16 v[26:29], v[178:181], v[210:213], v[26:29]
	v_mfma_f32_16x16x32_bf16 v[14:17], v[156:159], v[218:221], v[14:17]
	v_mfma_f32_16x16x32_bf16 v[10:13], v[178:181], v[218:221], v[10:13]
	v_mfma_f32_16x16x32_bf16 v[6:9], v[156:159], v[226:229], v[6:9]
	v_mfma_f32_16x16x32_bf16 v[2:5], v[178:181], v[226:229], v[2:5]
	v_mfma_f32_16x16x32_bf16 v[46:49], v[160:163], v[206:209], v[46:49]
	v_mfma_f32_16x16x32_bf16 v[42:45], v[182:185], v[206:209], v[42:45]
	v_mfma_f32_16x16x32_bf16 v[30:33], v[160:163], v[214:217], v[30:33]
	v_mfma_f32_16x16x32_bf16 v[26:29], v[182:185], v[214:217], v[26:29]
	v_mfma_f32_16x16x32_bf16 v[14:17], v[160:163], v[222:225], v[14:17]
	v_mfma_f32_16x16x32_bf16 v[10:13], v[182:185], v[222:225], v[10:13]
	v_mfma_f32_16x16x32_bf16 v[6:9], v[160:163], v[230:233], v[6:9]
	v_mfma_f32_16x16x32_bf16 v[2:5], v[182:185], v[230:233], v[2:5]
	s_barrier
	s_setprio 0
	v_add_u32_e32 v139, s97, v136
	ds_read_b128 v[140:143], v139
	ds_read_b128 v[144:147], v139 offset:1024
	ds_read_b128 v[148:151], v139 offset:2048
	ds_read_b128 v[152:155], v139 offset:3072
	v_add_u32_e32 v139, s96, v136
	ds_read_b128 v[156:159], v139
	ds_read_b128 v[160:163], v139 offset:1024
	ds_read_b128 v[178:181], v139 offset:2048
	ds_read_b128 v[182:185], v139 offset:3072
	s_mov_b32 m0, s87
	v_lshl_add_u64 v[244:245], s[72:73], 0, v[134:135]
	ds_read_b128 v[186:189], v138 offset:32768
	ds_read_b128 v[206:209], v138 offset:33792
	ds_read_b128 v[210:213], v138 offset:34816
	ds_read_b128 v[214:217], v138 offset:35840
	ds_read_b128 v[218:221], v138 offset:36864
	ds_read_b128 v[222:225], v138 offset:37888
	ds_read_b128 v[226:229], v138 offset:38912
	ds_read_b128 v[230:233], v138 offset:39936
	global_load_lds_dwordx4 v[244:245], off
	v_lshl_add_u64 v[244:245], s[72:73], 0, v[132:133]
	s_mov_b32 m0, s88
	s_nop 0
	global_load_lds_dwordx4 v[244:245], off
	s_waitcnt vmcnt(8)
	s_waitcnt lgkmcnt(0)
	s_setprio 1
	s_waitcnt lgkmcnt(0)
	v_mfma_f32_16x16x32_bf16 v[126:129], v[140:143], v[186:189], v[126:129]
	v_mfma_f32_16x16x32_bf16 v[122:125], v[148:151], v[186:189], v[122:125]
	v_mfma_f32_16x16x32_bf16 v[118:121], v[140:143], v[210:213], v[118:121]
	v_mfma_f32_16x16x32_bf16 v[114:117], v[148:151], v[210:213], v[114:117]
	s_barrier
	v_mfma_f32_16x16x32_bf16 v[102:105], v[140:143], v[218:221], v[102:105]
	v_mfma_f32_16x16x32_bf16 v[98:101], v[148:151], v[218:221], v[98:101]
	v_mfma_f32_16x16x32_bf16 v[86:89], v[140:143], v[226:229], v[86:89]
	v_mfma_f32_16x16x32_bf16 v[82:85], v[148:151], v[226:229], v[82:85]
	v_mfma_f32_16x16x32_bf16 v[126:129], v[144:147], v[206:209], v[126:129]
	v_mfma_f32_16x16x32_bf16 v[122:125], v[152:155], v[206:209], v[122:125]
	v_mfma_f32_16x16x32_bf16 v[118:121], v[144:147], v[214:217], v[118:121]
	v_mfma_f32_16x16x32_bf16 v[114:117], v[152:155], v[214:217], v[114:117]
	v_mfma_f32_16x16x32_bf16 v[102:105], v[144:147], v[222:225], v[102:105]
	v_mfma_f32_16x16x32_bf16 v[98:101], v[152:155], v[222:225], v[98:101]
	v_mfma_f32_16x16x32_bf16 v[86:89], v[144:147], v[230:233], v[86:89]
	v_mfma_f32_16x16x32_bf16 v[82:85], v[152:155], v[230:233], v[82:85]
	v_mfma_f32_16x16x32_bf16 v[110:113], v[156:159], v[186:189], v[110:113]
	v_mfma_f32_16x16x32_bf16 v[106:109], v[178:181], v[186:189], v[106:109]
	v_mfma_f32_16x16x32_bf16 v[94:97], v[156:159], v[210:213], v[94:97]
	v_mfma_f32_16x16x32_bf16 v[90:93], v[178:181], v[210:213], v[90:93]
	v_mfma_f32_16x16x32_bf16 v[78:81], v[156:159], v[218:221], v[78:81]
	v_mfma_f32_16x16x32_bf16 v[74:77], v[178:181], v[218:221], v[74:77]
	v_mfma_f32_16x16x32_bf16 v[70:73], v[156:159], v[226:229], v[70:73]
	v_mfma_f32_16x16x32_bf16 v[66:69], v[178:181], v[226:229], v[66:69]
	v_mfma_f32_16x16x32_bf16 v[110:113], v[160:163], v[206:209], v[110:113]
	v_mfma_f32_16x16x32_bf16 v[106:109], v[182:185], v[206:209], v[106:109]
	v_mfma_f32_16x16x32_bf16 v[94:97], v[160:163], v[214:217], v[94:97]
	v_mfma_f32_16x16x32_bf16 v[90:93], v[182:185], v[214:217], v[90:93]
	v_mfma_f32_16x16x32_bf16 v[78:81], v[160:163], v[222:225], v[78:81]
	v_mfma_f32_16x16x32_bf16 v[74:77], v[182:185], v[222:225], v[74:77]
	v_mfma_f32_16x16x32_bf16 v[70:73], v[160:163], v[230:233], v[70:73]
	v_mfma_f32_16x16x32_bf16 v[66:69], v[182:185], v[230:233], v[66:69]
	s_barrier
	s_setprio 0
	s_mov_b32 m0, s95
	v_lshl_add_u64 v[164:165], v[164:165], 0, s[42:43]
	ds_read_b128 v[186:189], v138 offset:49152
	ds_read_b128 v[206:209], v138 offset:50176
	ds_read_b128 v[210:213], v138 offset:51200
	ds_read_b128 v[214:217], v138 offset:52224
	ds_read_b128 v[218:221], v138 offset:53248
	ds_read_b128 v[222:225], v138 offset:54272
	ds_read_b128 v[226:229], v138 offset:55296
	ds_read_b128 v[230:233], v138 offset:56320
	global_load_lds_dwordx4 v[164:165], off
	v_lshl_add_u64 v[164:165], v[234:235], 0, s[42:43]
	s_mov_b32 m0, s94
	s_nop 0
	global_load_lds_dwordx4 v[164:165], off
	v_lshl_add_u64 v[164:165], s[60:61], 0, v[166:167]
	s_mov_b32 m0, s47
	s_nop 0
	global_load_lds_dwordx4 v[164:165], off
	v_lshl_add_u64 v[164:165], s[60:61], 0, v[130:131]
	s_mov_b32 m0, s46
	s_nop 0
	global_load_lds_dwordx4 v[164:165], off
	v_lshl_add_u64 v[164:165], v[236:237], 0, s[42:43]
	s_mov_b32 m0, s89
	s_nop 0
	global_load_lds_dwordx4 v[164:165], off
	v_lshl_add_u64 v[164:165], v[242:243], 0, s[42:43]
	s_mov_b32 m0, s90
	s_nop 0
	global_load_lds_dwordx4 v[164:165], off
	s_waitcnt vmcnt(8)
	s_waitcnt lgkmcnt(0)
	s_setprio 1
	s_waitcnt lgkmcnt(0)
	v_mfma_f32_16x16x32_bf16 v[62:65], v[140:143], v[186:189], v[62:65]
	v_mfma_f32_16x16x32_bf16 v[58:61], v[148:151], v[186:189], v[58:61]
	v_mfma_f32_16x16x32_bf16 v[54:57], v[140:143], v[210:213], v[54:57]
	v_mfma_f32_16x16x32_bf16 v[50:53], v[148:151], v[210:213], v[50:53]
	s_barrier
	v_mfma_f32_16x16x32_bf16 v[38:41], v[140:143], v[218:221], v[38:41]
	v_mfma_f32_16x16x32_bf16 v[34:37], v[148:151], v[218:221], v[34:37]
	v_mfma_f32_16x16x32_bf16 v[22:25], v[140:143], v[226:229], v[22:25]
	v_mfma_f32_16x16x32_bf16 v[18:21], v[148:151], v[226:229], v[18:21]
	v_mfma_f32_16x16x32_bf16 v[62:65], v[144:147], v[206:209], v[62:65]
	v_mfma_f32_16x16x32_bf16 v[58:61], v[152:155], v[206:209], v[58:61]
	v_mfma_f32_16x16x32_bf16 v[54:57], v[144:147], v[214:217], v[54:57]
	v_mfma_f32_16x16x32_bf16 v[50:53], v[152:155], v[214:217], v[50:53]
	v_mfma_f32_16x16x32_bf16 v[38:41], v[144:147], v[222:225], v[38:41]
	v_mfma_f32_16x16x32_bf16 v[34:37], v[152:155], v[222:225], v[34:37]
	v_mfma_f32_16x16x32_bf16 v[22:25], v[144:147], v[230:233], v[22:25]
	v_mfma_f32_16x16x32_bf16 v[18:21], v[152:155], v[230:233], v[18:21]
	v_mfma_f32_16x16x32_bf16 v[46:49], v[156:159], v[186:189], v[46:49]
	v_mfma_f32_16x16x32_bf16 v[42:45], v[178:181], v[186:189], v[42:45]
	v_mfma_f32_16x16x32_bf16 v[30:33], v[156:159], v[210:213], v[30:33]
	v_mfma_f32_16x16x32_bf16 v[26:29], v[178:181], v[210:213], v[26:29]
	v_mfma_f32_16x16x32_bf16 v[14:17], v[156:159], v[218:221], v[14:17]
	v_mfma_f32_16x16x32_bf16 v[10:13], v[178:181], v[218:221], v[10:13]
	v_mfma_f32_16x16x32_bf16 v[6:9], v[156:159], v[226:229], v[6:9]
	v_mfma_f32_16x16x32_bf16 v[2:5], v[178:181], v[226:229], v[2:5]
	v_mfma_f32_16x16x32_bf16 v[46:49], v[160:163], v[206:209], v[46:49]
	v_mfma_f32_16x16x32_bf16 v[42:45], v[182:185], v[206:209], v[42:45]
	v_mfma_f32_16x16x32_bf16 v[30:33], v[160:163], v[214:217], v[30:33]
	v_mfma_f32_16x16x32_bf16 v[26:29], v[182:185], v[214:217], v[26:29]
	v_mfma_f32_16x16x32_bf16 v[14:17], v[160:163], v[222:225], v[14:17]
	v_mfma_f32_16x16x32_bf16 v[10:13], v[182:185], v[222:225], v[10:13]
	v_mfma_f32_16x16x32_bf16 v[6:9], v[160:163], v[230:233], v[6:9]
	v_mfma_f32_16x16x32_bf16 v[2:5], v[182:185], v[230:233], v[2:5]
	s_barrier
	s_setprio 0
	s_movk_i32 s72, 0x100
	s_andn2_b64 vcc, exec, s[70:71]
	s_mov_b64 s[60:61], -1
	s_mov_b64 s[70:71], 0
	s_cbranch_vccz .LBB0_442
	s_and_b64 vcc, exec, s[10:11]
	s_cbranch_vccz .LBB0_445
	s_barrier

.LBB0_795:
	s_add_u32 s46, s68, 0xfff80080
	s_addc_u32 s47, s69, -1
	s_add_i32 s48, 0, 0x10000
	s_cmp_eq_u32 s87, 28
	s_cselect_b32 s71, s19, s47
	s_cselect_b32 s70, s83, s46
	s_cselect_b32 s61, s17, s86
	s_cselect_b32 s60, s84, s85
	s_add_i32 s49, 0, 0x14000
	v_add_u32_e32 v156, s48, v1
	v_add_u32_e32 v164, s49, v1
	ds_read_b128 v[130:133], v156
	ds_read_b128 v[134:137], v156 offset:1024
	ds_read_b128 v[150:153], v156 offset:2048
	ds_read_b128 v[156:159], v156 offset:3072
	ds_read_b128 v[160:163], v164
	ds_read_b128 v[178:181], v164 offset:1024
	ds_read_b128 v[182:185], v164 offset:2048
	ds_read_b128 v[186:189], v164 offset:3072
	v_lshl_add_u64 v[164:165], s[68:69], 0, v[146:147]
	s_add_i32 m0, s67, 0xc000
	ds_read_b128 v[206:209], v155
	ds_read_b128 v[210:213], v155 offset:1024
	ds_read_b128 v[214:217], v155 offset:2048
	ds_read_b128 v[218:221], v155 offset:3072
	ds_read_b128 v[222:225], v155 offset:4096
	ds_read_b128 v[226:229], v155 offset:5120
	ds_read_b128 v[230:233], v155 offset:6144
	ds_read_b128 v[234:237], v155 offset:7168
	global_load_lds_dwordx4 v[164:165], off
	v_lshl_add_u64 v[164:165], s[68:69], 0, v[148:149]
	s_add_i32 m0, s67, 0xe000
	s_nop 0
	global_load_lds_dwordx4 v[164:165], off
	s_waitcnt vmcnt(8)
	s_waitcnt lgkmcnt(0)
	s_setprio 1
	s_waitcnt lgkmcnt(0)
	v_mfma_f32_16x16x32_bf16 v[126:129], v[130:133], v[206:209], v[126:129]
	v_mfma_f32_16x16x32_bf16 v[122:125], v[150:153], v[206:209], v[122:125]
	v_mfma_f32_16x16x32_bf16 v[118:121], v[130:133], v[214:217], v[118:121]
	v_mfma_f32_16x16x32_bf16 v[114:117], v[150:153], v[214:217], v[114:117]
	s_barrier
	v_mfma_f32_16x16x32_bf16 v[110:113], v[130:133], v[222:225], v[110:113]
	v_mfma_f32_16x16x32_bf16 v[106:109], v[150:153], v[222:225], v[106:109]
	v_mfma_f32_16x16x32_bf16 v[102:105], v[130:133], v[230:233], v[102:105]
	v_mfma_f32_16x16x32_bf16 v[98:101], v[150:153], v[230:233], v[98:101]
	v_mfma_f32_16x16x32_bf16 v[126:129], v[134:137], v[210:213], v[126:129]
	v_mfma_f32_16x16x32_bf16 v[122:125], v[156:159], v[210:213], v[122:125]
	v_mfma_f32_16x16x32_bf16 v[118:121], v[134:137], v[218:221], v[118:121]
	v_mfma_f32_16x16x32_bf16 v[114:117], v[156:159], v[218:221], v[114:117]
	v_mfma_f32_16x16x32_bf16 v[110:113], v[134:137], v[226:229], v[110:113]
	v_mfma_f32_16x16x32_bf16 v[106:109], v[156:159], v[226:229], v[106:109]
	v_mfma_f32_16x16x32_bf16 v[102:105], v[134:137], v[234:237], v[102:105]
	v_mfma_f32_16x16x32_bf16 v[98:101], v[156:159], v[234:237], v[98:101]
	v_mfma_f32_16x16x32_bf16 v[66:69], v[160:163], v[206:209], v[66:69]
	v_mfma_f32_16x16x32_bf16 v[58:61], v[182:185], v[206:209], v[58:61]
	v_mfma_f32_16x16x32_bf16 v[54:57], v[160:163], v[214:217], v[54:57]
	v_mfma_f32_16x16x32_bf16 v[50:53], v[182:185], v[214:217], v[50:53]
	v_mfma_f32_16x16x32_bf16 v[46:49], v[160:163], v[222:225], v[46:49]
	v_mfma_f32_16x16x32_bf16 v[42:45], v[182:185], v[222:225], v[42:45]
	v_mfma_f32_16x16x32_bf16 v[38:41], v[160:163], v[230:233], v[38:41]
	v_mfma_f32_16x16x32_bf16 v[34:37], v[182:185], v[230:233], v[34:37]
	v_mfma_f32_16x16x32_bf16 v[66:69], v[178:181], v[210:213], v[66:69]
	v_mfma_f32_16x16x32_bf16 v[58:61], v[186:189], v[210:213], v[58:61]
	v_mfma_f32_16x16x32_bf16 v[54:57], v[178:181], v[218:221], v[54:57]
	v_mfma_f32_16x16x32_bf16 v[50:53], v[186:189], v[218:221], v[50:53]
	v_mfma_f32_16x16x32_bf16 v[46:49], v[178:181], v[226:229], v[46:49]
	v_mfma_f32_16x16x32_bf16 v[42:45], v[186:189], v[226:229], v[42:45]
	v_mfma_f32_16x16x32_bf16 v[38:41], v[178:181], v[234:237], v[38:41]
	v_mfma_f32_16x16x32_bf16 v[34:37], v[186:189], v[234:237], v[34:37]
	s_barrier
	s_setprio 0
	s_add_i32 s46, s48, s77
	v_lshl_add_u64 v[164:165], s[60:61], 0, v[166:167]
	s_mov_b32 m0, s46
	ds_read_b128 v[206:209], v155 offset:16384
	ds_read_b128 v[210:213], v155 offset:17408
	ds_read_b128 v[214:217], v155 offset:18432
	ds_read_b128 v[218:221], v155 offset:19456
	ds_read_b128 v[222:225], v155 offset:20480
	ds_read_b128 v[226:229], v155 offset:21504
	ds_read_b128 v[230:233], v155 offset:22528
	ds_read_b128 v[234:237], v155 offset:23552
	global_load_lds_dwordx4 v[164:165], off
	s_add_i32 m0, s46, 0x2000
	s_add_u32 s46, s60, 0x80000
	v_lshl_add_u64 v[242:243], s[60:61], 0, v[142:143]
	s_addc_u32 s47, s61, 0
	s_add_i32 s48, s49, s77
	global_load_lds_dwordx4 v[242:243], off
	v_lshl_add_u64 v[244:245], s[46:47], 0, v[166:167]
	s_mov_b32 m0, s48
	v_lshl_add_u64 v[246:247], s[70:71], 0, v[140:141]
	global_load_lds_dwordx4 v[244:245], off
	v_lshl_add_u64 v[244:245], s[46:47], 0, v[142:143]
	s_add_i32 m0, s48, 0x2000
	s_nop 0
	global_load_lds_dwordx4 v[244:245], off
	v_lshl_add_u64 v[244:245], s[70:71], 0, v[138:139]
	s_mov_b32 m0, s67
	s_nop 0
	global_load_lds_dwordx4 v[244:245], off
	s_mov_b32 m0, s78
	s_nop 0
	global_load_lds_dwordx4 v[246:247], off
	s_waitcnt vmcnt(8)
	s_waitcnt lgkmcnt(0)
	s_setprio 1
	s_waitcnt lgkmcnt(0)
	v_mfma_f32_16x16x32_bf16 v[94:97], v[130:133], v[206:209], v[94:97]
	v_mfma_f32_16x16x32_bf16 v[90:93], v[150:153], v[206:209], v[90:93]
	v_mfma_f32_16x16x32_bf16 v[86:89], v[130:133], v[214:217], v[86:89]
	v_mfma_f32_16x16x32_bf16 v[82:85], v[150:153], v[214:217], v[82:85]
	s_barrier
	v_mfma_f32_16x16x32_bf16 v[78:81], v[130:133], v[222:225], v[78:81]
	v_mfma_f32_16x16x32_bf16 v[74:77], v[150:153], v[222:225], v[74:77]
	v_mfma_f32_16x16x32_bf16 v[70:73], v[130:133], v[230:233], v[70:73]
	v_mfma_f32_16x16x32_bf16 v[62:65], v[150:153], v[230:233], v[62:65]
	v_mfma_f32_16x16x32_bf16 v[94:97], v[134:137], v[210:213], v[94:97]
	v_mfma_f32_16x16x32_bf16 v[90:93], v[156:159], v[210:213], v[90:93]
	v_mfma_f32_16x16x32_bf16 v[86:89], v[134:137], v[218:221], v[86:89]
	v_mfma_f32_16x16x32_bf16 v[82:85], v[156:159], v[218:221], v[82:85]
	v_mfma_f32_16x16x32_bf16 v[78:81], v[134:137], v[226:229], v[78:81]
	v_mfma_f32_16x16x32_bf16 v[74:77], v[156:159], v[226:229], v[74:77]
	v_mfma_f32_16x16x32_bf16 v[70:73], v[134:137], v[234:237], v[70:73]
	v_mfma_f32_16x16x32_bf16 v[62:65], v[156:159], v[234:237], v[62:65]
	v_mfma_f32_16x16x32_bf16 v[30:33], v[160:163], v[206:209], v[30:33]
	v_mfma_f32_16x16x32_bf16 v[26:29], v[182:185], v[206:209], v[26:29]
	v_mfma_f32_16x16x32_bf16 v[22:25], v[160:163], v[214:217], v[22:25]
	v_mfma_f32_16x16x32_bf16 v[18:21], v[182:185], v[214:217], v[18:21]
	v_mfma_f32_16x16x32_bf16 v[14:17], v[160:163], v[222:225], v[14:17]
	v_mfma_f32_16x16x32_bf16 v[10:13], v[182:185], v[222:225], v[10:13]
	v_mfma_f32_16x16x32_bf16 v[6:9], v[160:163], v[230:233], v[6:9]
	v_mfma_f32_16x16x32_bf16 v[2:5], v[182:185], v[230:233], v[2:5]
	v_mfma_f32_16x16x32_bf16 v[30:33], v[178:181], v[210:213], v[30:33]
	v_mfma_f32_16x16x32_bf16 v[26:29], v[186:189], v[210:213], v[26:29]
	v_mfma_f32_16x16x32_bf16 v[22:25], v[178:181], v[218:221], v[22:25]
	v_mfma_f32_16x16x32_bf16 v[18:21], v[186:189], v[218:221], v[18:21]
	v_mfma_f32_16x16x32_bf16 v[14:17], v[178:181], v[226:229], v[14:17]
	v_mfma_f32_16x16x32_bf16 v[10:13], v[186:189], v[226:229], v[10:13]
	v_mfma_f32_16x16x32_bf16 v[6:9], v[178:181], v[234:237], v[6:9]
	v_mfma_f32_16x16x32_bf16 v[2:5], v[186:189], v[234:237], v[2:5]
	s_barrier
	s_setprio 0
	s_add_i32 s48, 0, 0x18000
	s_add_i32 s49, 0, 0x1c000
	v_add_u32_e32 v156, s48, v1
	v_add_u32_e32 v186, s49, v1
	ds_read_b128 v[130:133], v156
	ds_read_b128 v[134:137], v156 offset:1024
	ds_read_b128 v[150:153], v156 offset:2048
	ds_read_b128 v[156:159], v156 offset:3072
	ds_read_b128 v[160:163], v186
	ds_read_b128 v[178:181], v186 offset:1024
	ds_read_b128 v[182:185], v186 offset:2048
	ds_read_b128 v[186:189], v186 offset:3072
	s_add_u32 s46, s70, 0x80000
	s_addc_u32 s47, s71, 0
	s_mov_b32 m0, s79
	v_lshl_add_u64 v[248:249], s[46:47], 0, v[138:139]
	ds_read_b128 v[206:209], v155 offset:32768
	ds_read_b128 v[210:213], v155 offset:33792
	ds_read_b128 v[214:217], v155 offset:34816
	ds_read_b128 v[218:221], v155 offset:35840
	ds_read_b128 v[222:225], v155 offset:36864
	ds_read_b128 v[226:229], v155 offset:37888
	ds_read_b128 v[230:233], v155 offset:38912
	ds_read_b128 v[234:237], v155 offset:39936
	global_load_lds_dwordx4 v[248:249], off
	v_lshl_add_u64 v[248:249], s[46:47], 0, v[140:141]
	s_mov_b32 m0, s80
	s_nop 0
	global_load_lds_dwordx4 v[248:249], off
	s_waitcnt vmcnt(8)
	s_waitcnt lgkmcnt(0)
	s_setprio 1
	s_waitcnt lgkmcnt(0)
	v_mfma_f32_16x16x32_bf16 v[126:129], v[130:133], v[206:209], v[126:129]
	v_mfma_f32_16x16x32_bf16 v[122:125], v[150:153], v[206:209], v[122:125]
	v_mfma_f32_16x16x32_bf16 v[118:121], v[130:133], v[214:217], v[118:121]
	v_mfma_f32_16x16x32_bf16 v[114:117], v[150:153], v[214:217], v[114:117]
	s_barrier
	v_mfma_f32_16x16x32_bf16 v[110:113], v[130:133], v[222:225], v[110:113]
	v_mfma_f32_16x16x32_bf16 v[106:109], v[150:153], v[222:225], v[106:109]
	v_mfma_f32_16x16x32_bf16 v[102:105], v[130:133], v[230:233], v[102:105]
	v_mfma_f32_16x16x32_bf16 v[98:101], v[150:153], v[230:233], v[98:101]
	v_mfma_f32_16x16x32_bf16 v[126:129], v[134:137], v[210:213], v[126:129]
	v_mfma_f32_16x16x32_bf16 v[122:125], v[156:159], v[210:213], v[122:125]
	v_mfma_f32_16x16x32_bf16 v[118:121], v[134:137], v[218:221], v[118:121]
	v_mfma_f32_16x16x32_bf16 v[114:117], v[156:159], v[218:221], v[114:117]
	v_mfma_f32_16x16x32_bf16 v[110:113], v[134:137], v[226:229], v[110:113]
	v_mfma_f32_16x16x32_bf16 v[106:109], v[156:159], v[226:229], v[106:109]
	v_mfma_f32_16x16x32_bf16 v[102:105], v[134:137], v[234:237], v[102:105]
	v_mfma_f32_16x16x32_bf16 v[98:101], v[156:159], v[234:237], v[98:101]
	v_mfma_f32_16x16x32_bf16 v[66:69], v[160:163], v[206:209], v[66:69]
	v_mfma_f32_16x16x32_bf16 v[58:61], v[182:185], v[206:209], v[58:61]
	v_mfma_f32_16x16x32_bf16 v[54:57], v[160:163], v[214:217], v[54:57]
	v_mfma_f32_16x16x32_bf16 v[50:53], v[182:185], v[214:217], v[50:53]
	v_mfma_f32_16x16x32_bf16 v[46:49], v[160:163], v[222:225], v[46:49]
	v_mfma_f32_16x16x32_bf16 v[42:45], v[182:185], v[222:225], v[42:45]
	v_mfma_f32_16x16x32_bf16 v[38:41], v[160:163], v[230:233], v[38:41]
	v_mfma_f32_16x16x32_bf16 v[34:37], v[182:185], v[230:233], v[34:37]
	v_mfma_f32_16x16x32_bf16 v[66:69], v[178:181], v[210:213], v[66:69]
	v_mfma_f32_16x16x32_bf16 v[58:61], v[186:189], v[210:213], v[58:61]
	v_mfma_f32_16x16x32_bf16 v[54:57], v[178:181], v[218:221], v[54:57]
	v_mfma_f32_16x16x32_bf16 v[50:53], v[186:189], v[218:221], v[50:53]
	v_mfma_f32_16x16x32_bf16 v[46:49], v[178:181], v[226:229], v[46:49]
	v_mfma_f32_16x16x32_bf16 v[42:45], v[186:189], v[226:229], v[42:45]
	v_mfma_f32_16x16x32_bf16 v[38:41], v[178:181], v[234:237], v[38:41]
	v_mfma_f32_16x16x32_bf16 v[34:37], v[186:189], v[234:237], v[34:37]
	s_barrier
	s_setprio 0
	s_add_i32 s46, s48, s77
	v_lshl_add_u64 v[164:165], v[164:165], 0, s[42:43]
	s_mov_b32 m0, s46
	ds_read_b128 v[206:209], v155 offset:49152
	ds_read_b128 v[210:213], v155 offset:50176
	ds_read_b128 v[214:217], v155 offset:51200
	ds_read_b128 v[218:221], v155 offset:52224
	ds_read_b128 v[222:225], v155 offset:53248
	ds_read_b128 v[226:229], v155 offset:54272
	ds_read_b128 v[230:233], v155 offset:55296
	ds_read_b128 v[234:237], v155 offset:56320
	global_load_lds_dwordx4 v[164:165], off
	s_add_i32 m0, s46, 0x2000
	s_add_u32 s46, s60, 0x80080
	v_lshl_add_u64 v[164:165], v[242:243], 0, s[42:43]
	s_addc_u32 s47, s61, 0
	s_add_i32 s48, s49, s77
	global_load_lds_dwordx4 v[164:165], off
	v_lshl_add_u64 v[164:165], s[46:47], 0, v[166:167]
	s_mov_b32 m0, s48
	s_nop 0
	global_load_lds_dwordx4 v[164:165], off
	v_lshl_add_u64 v[164:165], s[46:47], 0, v[142:143]
	s_add_i32 m0, s48, 0x2000
	s_nop 0
	global_load_lds_dwordx4 v[164:165], off
	v_lshl_add_u64 v[164:165], v[244:245], 0, s[42:43]
	s_mov_b32 m0, s26
	s_nop 0
	global_load_lds_dwordx4 v[164:165], off
	v_lshl_add_u64 v[164:165], v[246:247], 0, s[42:43]
	s_mov_b32 m0, s81
	s_nop 0
	global_load_lds_dwordx4 v[164:165], off
	s_waitcnt vmcnt(8)
	s_waitcnt lgkmcnt(0)
	s_setprio 1
	s_waitcnt lgkmcnt(0)
	v_mfma_f32_16x16x32_bf16 v[94:97], v[130:133], v[206:209], v[94:97]
	v_mfma_f32_16x16x32_bf16 v[90:93], v[150:153], v[206:209], v[90:93]
	v_mfma_f32_16x16x32_bf16 v[86:89], v[130:133], v[214:217], v[86:89]
	v_mfma_f32_16x16x32_bf16 v[82:85], v[150:153], v[214:217], v[82:85]
	s_barrier
	v_mfma_f32_16x16x32_bf16 v[78:81], v[130:133], v[222:225], v[78:81]
	v_mfma_f32_16x16x32_bf16 v[74:77], v[150:153], v[222:225], v[74:77]
	v_mfma_f32_16x16x32_bf16 v[70:73], v[130:133], v[230:233], v[70:73]
	v_mfma_f32_16x16x32_bf16 v[62:65], v[150:153], v[230:233], v[62:65]
	v_mfma_f32_16x16x32_bf16 v[94:97], v[134:137], v[210:213], v[94:97]
	v_mfma_f32_16x16x32_bf16 v[90:93], v[156:159], v[210:213], v[90:93]
	v_mfma_f32_16x16x32_bf16 v[86:89], v[134:137], v[218:221], v[86:89]
	v_mfma_f32_16x16x32_bf16 v[82:85], v[156:159], v[218:221], v[82:85]
	v_mfma_f32_16x16x32_bf16 v[78:81], v[134:137], v[226:229], v[78:81]
	v_mfma_f32_16x16x32_bf16 v[74:77], v[156:159], v[226:229], v[74:77]
	v_mfma_f32_16x16x32_bf16 v[70:73], v[134:137], v[234:237], v[70:73]
	v_mfma_f32_16x16x32_bf16 v[62:65], v[156:159], v[234:237], v[62:65]
	v_mfma_f32_16x16x32_bf16 v[30:33], v[160:163], v[206:209], v[30:33]
	v_mfma_f32_16x16x32_bf16 v[26:29], v[182:185], v[206:209], v[26:29]
	v_mfma_f32_16x16x32_bf16 v[22:25], v[160:163], v[214:217], v[22:25]
	v_mfma_f32_16x16x32_bf16 v[18:21], v[182:185], v[214:217], v[18:21]
	v_mfma_f32_16x16x32_bf16 v[14:17], v[160:163], v[222:225], v[14:17]
	v_mfma_f32_16x16x32_bf16 v[10:13], v[182:185], v[222:225], v[10:13]
	v_mfma_f32_16x16x32_bf16 v[6:9], v[160:163], v[230:233], v[6:9]
	v_mfma_f32_16x16x32_bf16 v[2:5], v[182:185], v[230:233], v[2:5]
	v_mfma_f32_16x16x32_bf16 v[30:33], v[178:181], v[210:213], v[30:33]
	v_mfma_f32_16x16x32_bf16 v[26:29], v[186:189], v[210:213], v[26:29]
	v_mfma_f32_16x16x32_bf16 v[22:25], v[178:181], v[218:221], v[22:25]
	v_mfma_f32_16x16x32_bf16 v[18:21], v[186:189], v[218:221], v[18:21]
	v_mfma_f32_16x16x32_bf16 v[14:17], v[178:181], v[226:229], v[14:17]
	v_mfma_f32_16x16x32_bf16 v[10:13], v[186:189], v[226:229], v[10:13]
	v_mfma_f32_16x16x32_bf16 v[6:9], v[178:181], v[234:237], v[6:9]
	v_mfma_f32_16x16x32_bf16 v[2:5], v[186:189], v[234:237], v[2:5]
	s_barrier
	s_setprio 0
	s_add_i32 s87, s87, 2
	s_add_u32 s68, s68, 0x100
	s_addc_u32 s69, s69, 0
	s_add_u32 s85, s85, 0x100
	s_addc_u32 s86, s86, 0
	s_cmp_gt_u32 s87, 29
	s_cbranch_scc0 .LBB0_795
	s_and_b64 vcc, exec, s[12:13]
	s_cbranch_vccz .LBB0_798
	s_barrier

.LBB0_819:
	s_add_i32 s93, s60, 2
	s_add_u32 s46, s72, 0x80
	s_addc_u32 s47, s73, 0
	s_add_i32 s48, 0, 0x10000
	s_cmp_eq_u32 s87, s60
	s_cselect_b32 s61, s23, s47
	s_cselect_b32 s60, s64, s46
	s_cselect_b32 s47, s21, s92
	s_cselect_b32 s46, s90, s91
	s_add_i32 s49, 0, 0x14000
	v_add_u32_e32 v142, s48, v205
	v_add_u32_e32 v182, s49, v205
	ds_read_b128 v[130:133], v142
	ds_read_b128 v[134:137], v142 offset:1024
	ds_read_b128 v[138:141], v142 offset:2048
	ds_read_b128 v[142:145], v142 offset:3072
	ds_read_b128 v[146:149], v182
	ds_read_b128 v[150:153], v182 offset:1024
	ds_read_b128 v[178:181], v182 offset:2048
	ds_read_b128 v[182:185], v182 offset:3072
	v_lshl_add_u64 v[236:237], s[72:73], 0, v[162:163]
	s_add_i32 m0, s71, 0xc000
	ds_read_b128 v[186:189], v207
	ds_read_b128 v[208:211], v207 offset:1024
	ds_read_b128 v[212:215], v207 offset:2048
	ds_read_b128 v[216:219], v207 offset:3072
	ds_read_b128 v[220:223], v207 offset:4096
	ds_read_b128 v[224:227], v207 offset:5120
	ds_read_b128 v[228:231], v207 offset:6144
	ds_read_b128 v[232:235], v207 offset:7168
	global_load_lds_dwordx4 v[236:237], off
	v_lshl_add_u64 v[236:237], s[72:73], 0, v[164:165]
	s_add_i32 m0, s71, 0xe000
	s_nop 0
	global_load_lds_dwordx4 v[236:237], off
	s_waitcnt vmcnt(8)
	s_waitcnt lgkmcnt(0)
	s_setprio 1
	s_waitcnt lgkmcnt(0)
	v_mfma_f32_16x16x32_bf16 v[126:129], v[130:133], v[186:189], v[126:129]
	v_mfma_f32_16x16x32_bf16 v[122:125], v[138:141], v[186:189], v[122:125]
	v_mfma_f32_16x16x32_bf16 v[118:121], v[130:133], v[212:215], v[118:121]
	v_mfma_f32_16x16x32_bf16 v[114:117], v[138:141], v[212:215], v[114:117]
	s_barrier
	v_mfma_f32_16x16x32_bf16 v[110:113], v[130:133], v[220:223], v[110:113]
	v_mfma_f32_16x16x32_bf16 v[106:109], v[138:141], v[220:223], v[106:109]
	v_mfma_f32_16x16x32_bf16 v[102:105], v[130:133], v[228:231], v[102:105]
	v_mfma_f32_16x16x32_bf16 v[98:101], v[138:141], v[228:231], v[98:101]
	v_mfma_f32_16x16x32_bf16 v[126:129], v[134:137], v[208:211], v[126:129]
	v_mfma_f32_16x16x32_bf16 v[122:125], v[142:145], v[208:211], v[122:125]
	v_mfma_f32_16x16x32_bf16 v[118:121], v[134:137], v[216:219], v[118:121]
	v_mfma_f32_16x16x32_bf16 v[114:117], v[142:145], v[216:219], v[114:117]
	v_mfma_f32_16x16x32_bf16 v[110:113], v[134:137], v[224:227], v[110:113]
	v_mfma_f32_16x16x32_bf16 v[106:109], v[142:145], v[224:227], v[106:109]
	v_mfma_f32_16x16x32_bf16 v[102:105], v[134:137], v[232:235], v[102:105]
	v_mfma_f32_16x16x32_bf16 v[98:101], v[142:145], v[232:235], v[98:101]
	v_mfma_f32_16x16x32_bf16 v[94:97], v[146:149], v[186:189], v[94:97]
	v_mfma_f32_16x16x32_bf16 v[90:93], v[178:181], v[186:189], v[90:93]
	v_mfma_f32_16x16x32_bf16 v[86:89], v[146:149], v[212:215], v[86:89]
	v_mfma_f32_16x16x32_bf16 v[82:85], v[178:181], v[212:215], v[82:85]
	v_mfma_f32_16x16x32_bf16 v[78:81], v[146:149], v[220:223], v[78:81]
	v_mfma_f32_16x16x32_bf16 v[74:77], v[178:181], v[220:223], v[74:77]
	v_mfma_f32_16x16x32_bf16 v[70:73], v[146:149], v[228:231], v[70:73]
	v_mfma_f32_16x16x32_bf16 v[66:69], v[178:181], v[228:231], v[66:69]
	v_mfma_f32_16x16x32_bf16 v[94:97], v[150:153], v[208:211], v[94:97]
	v_mfma_f32_16x16x32_bf16 v[90:93], v[182:185], v[208:211], v[90:93]
	v_mfma_f32_16x16x32_bf16 v[86:89], v[150:153], v[216:219], v[86:89]
	v_mfma_f32_16x16x32_bf16 v[82:85], v[182:185], v[216:219], v[82:85]
	v_mfma_f32_16x16x32_bf16 v[78:81], v[150:153], v[224:227], v[78:81]
	v_mfma_f32_16x16x32_bf16 v[74:77], v[182:185], v[224:227], v[74:77]
	v_mfma_f32_16x16x32_bf16 v[70:73], v[150:153], v[232:235], v[70:73]
	v_mfma_f32_16x16x32_bf16 v[66:69], v[182:185], v[232:235], v[66:69]
	s_barrier
	s_setprio 0
	s_add_i32 s48, s48, s80
	v_lshl_add_u64 v[236:237], s[46:47], 0, v[166:167]
	s_mov_b32 m0, s48
	ds_read_b128 v[186:189], v207 offset:16384
	ds_read_b128 v[208:211], v207 offset:17408
	ds_read_b128 v[212:215], v207 offset:18432
	ds_read_b128 v[216:219], v207 offset:19456
	ds_read_b128 v[220:223], v207 offset:20480
	ds_read_b128 v[224:227], v207 offset:21504
	ds_read_b128 v[228:231], v207 offset:22528
	ds_read_b128 v[232:235], v207 offset:23552
	global_load_lds_dwordx4 v[236:237], off
	s_add_i32 m0, s48, 0x2000
	v_lshl_add_u64 v[242:243], s[46:47], 0, v[158:159]
	s_add_u32 s46, s46, s26
	s_addc_u32 s47, s47, 0
	s_add_i32 s48, s49, s80
	global_load_lds_dwordx4 v[242:243], off
	v_lshl_add_u64 v[244:245], s[46:47], 0, v[166:167]
	s_mov_b32 m0, s48
	v_lshl_add_u64 v[246:247], s[46:47], 0, v[158:159]
	global_load_lds_dwordx4 v[244:245], off
	s_add_i32 m0, s48, 0x2000
	v_lshl_add_u64 v[248:249], s[60:61], 0, v[154:155]
	global_load_lds_dwordx4 v[246:247], off
	s_mov_b32 m0, s71
	v_lshl_add_u64 v[250:251], s[60:61], 0, v[156:157]
	global_load_lds_dwordx4 v[248:249], off
	s_mov_b32 m0, s81
	s_nop 0
	global_load_lds_dwordx4 v[250:251], off
	s_waitcnt vmcnt(8)
	s_waitcnt lgkmcnt(0)
	s_setprio 1
	s_waitcnt lgkmcnt(0)
	v_mfma_f32_16x16x32_bf16 v[62:65], v[130:133], v[186:189], v[62:65]
	v_mfma_f32_16x16x32_bf16 v[58:61], v[138:141], v[186:189], v[58:61]
	v_mfma_f32_16x16x32_bf16 v[54:57], v[130:133], v[212:215], v[54:57]
	v_mfma_f32_16x16x32_bf16 v[50:53], v[138:141], v[212:215], v[50:53]
	s_barrier
	v_mfma_f32_16x16x32_bf16 v[46:49], v[130:133], v[220:223], v[46:49]
	v_mfma_f32_16x16x32_bf16 v[42:45], v[138:141], v[220:223], v[42:45]
	v_mfma_f32_16x16x32_bf16 v[38:41], v[130:133], v[228:231], v[38:41]
	v_mfma_f32_16x16x32_bf16 v[34:37], v[138:141], v[228:231], v[34:37]
	v_mfma_f32_16x16x32_bf16 v[62:65], v[134:137], v[208:211], v[62:65]
	v_mfma_f32_16x16x32_bf16 v[58:61], v[142:145], v[208:211], v[58:61]
	v_mfma_f32_16x16x32_bf16 v[54:57], v[134:137], v[216:219], v[54:57]
	v_mfma_f32_16x16x32_bf16 v[50:53], v[142:145], v[216:219], v[50:53]
	v_mfma_f32_16x16x32_bf16 v[46:49], v[134:137], v[224:227], v[46:49]
	v_mfma_f32_16x16x32_bf16 v[42:45], v[142:145], v[224:227], v[42:45]
	v_mfma_f32_16x16x32_bf16 v[38:41], v[134:137], v[232:235], v[38:41]
	v_mfma_f32_16x16x32_bf16 v[34:37], v[142:145], v[232:235], v[34:37]
	v_mfma_f32_16x16x32_bf16 v[30:33], v[146:149], v[186:189], v[30:33]
	v_mfma_f32_16x16x32_bf16 v[26:29], v[178:181], v[186:189], v[26:29]
	v_mfma_f32_16x16x32_bf16 v[22:25], v[146:149], v[212:215], v[22:25]
	v_mfma_f32_16x16x32_bf16 v[18:21], v[178:181], v[212:215], v[18:21]
	v_mfma_f32_16x16x32_bf16 v[14:17], v[146:149], v[220:223], v[14:17]
	v_mfma_f32_16x16x32_bf16 v[10:13], v[178:181], v[220:223], v[10:13]
	v_mfma_f32_16x16x32_bf16 v[6:9], v[146:149], v[228:231], v[6:9]
	v_mfma_f32_16x16x32_bf16 v[2:5], v[178:181], v[228:231], v[2:5]
	v_mfma_f32_16x16x32_bf16 v[30:33], v[150:153], v[208:211], v[30:33]
	v_mfma_f32_16x16x32_bf16 v[26:29], v[182:185], v[208:211], v[26:29]
	v_mfma_f32_16x16x32_bf16 v[22:25], v[150:153], v[216:219], v[22:25]
	v_mfma_f32_16x16x32_bf16 v[18:21], v[182:185], v[216:219], v[18:21]
	v_mfma_f32_16x16x32_bf16 v[14:17], v[150:153], v[224:227], v[14:17]
	v_mfma_f32_16x16x32_bf16 v[10:13], v[182:185], v[224:227], v[10:13]
	v_mfma_f32_16x16x32_bf16 v[6:9], v[150:153], v[232:235], v[6:9]
	v_mfma_f32_16x16x32_bf16 v[2:5], v[182:185], v[232:235], v[2:5]
	s_barrier
	s_setprio 0
	s_add_i32 s48, 0, 0x18000
	s_add_i32 s49, 0, 0x1c000
	v_add_u32_e32 v142, s48, v205
	v_add_u32_e32 v182, s49, v205
	ds_read_b128 v[130:133], v142
	ds_read_b128 v[134:137], v142 offset:1024
	ds_read_b128 v[138:141], v142 offset:2048
	ds_read_b128 v[142:145], v142 offset:3072
	ds_read_b128 v[146:149], v182
	ds_read_b128 v[150:153], v182 offset:1024
	ds_read_b128 v[178:181], v182 offset:2048
	ds_read_b128 v[182:185], v182 offset:3072
	s_add_u32 s46, s60, s26
	s_addc_u32 s47, s61, 0
	s_mov_b32 m0, s82
	v_lshl_add_u64 v[252:253], s[46:47], 0, v[154:155]
	ds_read_b128 v[186:189], v207 offset:32768
	ds_read_b128 v[208:211], v207 offset:33792
	ds_read_b128 v[212:215], v207 offset:34816
	ds_read_b128 v[216:219], v207 offset:35840
	ds_read_b128 v[220:223], v207 offset:36864
	ds_read_b128 v[224:227], v207 offset:37888
	ds_read_b128 v[228:231], v207 offset:38912
	ds_read_b128 v[232:235], v207 offset:39936
	global_load_lds_dwordx4 v[252:253], off
	v_lshl_add_u64 v[252:253], s[46:47], 0, v[156:157]
	s_mov_b32 m0, s83
	s_nop 0
	global_load_lds_dwordx4 v[252:253], off
	s_waitcnt vmcnt(8)
	s_waitcnt lgkmcnt(0)
	s_setprio 1
	s_waitcnt lgkmcnt(0)
	v_mfma_f32_16x16x32_bf16 v[126:129], v[130:133], v[186:189], v[126:129]
	v_mfma_f32_16x16x32_bf16 v[122:125], v[138:141], v[186:189], v[122:125]
	v_mfma_f32_16x16x32_bf16 v[118:121], v[130:133], v[212:215], v[118:121]
	v_mfma_f32_16x16x32_bf16 v[114:117], v[138:141], v[212:215], v[114:117]
	s_barrier
	v_mfma_f32_16x16x32_bf16 v[110:113], v[130:133], v[220:223], v[110:113]
	v_mfma_f32_16x16x32_bf16 v[106:109], v[138:141], v[220:223], v[106:109]
	v_mfma_f32_16x16x32_bf16 v[102:105], v[130:133], v[228:231], v[102:105]
	v_mfma_f32_16x16x32_bf16 v[98:101], v[138:141], v[228:231], v[98:101]
	v_mfma_f32_16x16x32_bf16 v[126:129], v[134:137], v[208:211], v[126:129]
	v_mfma_f32_16x16x32_bf16 v[122:125], v[142:145], v[208:211], v[122:125]
	v_mfma_f32_16x16x32_bf16 v[118:121], v[134:137], v[216:219], v[118:121]
	v_mfma_f32_16x16x32_bf16 v[114:117], v[142:145], v[216:219], v[114:117]
	v_mfma_f32_16x16x32_bf16 v[110:113], v[134:137], v[224:227], v[110:113]
	v_mfma_f32_16x16x32_bf16 v[106:109], v[142:145], v[224:227], v[106:109]
	v_mfma_f32_16x16x32_bf16 v[102:105], v[134:137], v[232:235], v[102:105]
	v_mfma_f32_16x16x32_bf16 v[98:101], v[142:145], v[232:235], v[98:101]
	v_mfma_f32_16x16x32_bf16 v[94:97], v[146:149], v[186:189], v[94:97]
	v_mfma_f32_16x16x32_bf16 v[90:93], v[178:181], v[186:189], v[90:93]
	v_mfma_f32_16x16x32_bf16 v[86:89], v[146:149], v[212:215], v[86:89]
	v_mfma_f32_16x16x32_bf16 v[82:85], v[178:181], v[212:215], v[82:85]
	v_mfma_f32_16x16x32_bf16 v[78:81], v[146:149], v[220:223], v[78:81]
	v_mfma_f32_16x16x32_bf16 v[74:77], v[178:181], v[220:223], v[74:77]
	v_mfma_f32_16x16x32_bf16 v[70:73], v[146:149], v[228:231], v[70:73]
	v_mfma_f32_16x16x32_bf16 v[66:69], v[178:181], v[228:231], v[66:69]
	v_mfma_f32_16x16x32_bf16 v[94:97], v[150:153], v[208:211], v[94:97]
	v_mfma_f32_16x16x32_bf16 v[90:93], v[182:185], v[208:211], v[90:93]
	v_mfma_f32_16x16x32_bf16 v[86:89], v[150:153], v[216:219], v[86:89]
	v_mfma_f32_16x16x32_bf16 v[82:85], v[182:185], v[216:219], v[82:85]
	v_mfma_f32_16x16x32_bf16 v[78:81], v[150:153], v[224:227], v[78:81]
	v_mfma_f32_16x16x32_bf16 v[74:77], v[182:185], v[224:227], v[74:77]
	v_mfma_f32_16x16x32_bf16 v[70:73], v[150:153], v[232:235], v[70:73]
	v_mfma_f32_16x16x32_bf16 v[66:69], v[182:185], v[232:235], v[66:69]
	s_barrier
	s_setprio 0
	s_add_i32 s46, s48, s80
	v_lshl_add_u64 v[236:237], v[236:237], 0, s[42:43]
	s_mov_b32 m0, s46
	ds_read_b128 v[186:189], v207 offset:49152
	ds_read_b128 v[208:211], v207 offset:50176
	ds_read_b128 v[212:215], v207 offset:51200
	ds_read_b128 v[216:219], v207 offset:52224
	ds_read_b128 v[220:223], v207 offset:53248
	ds_read_b128 v[224:227], v207 offset:54272
	ds_read_b128 v[228:231], v207 offset:55296
	ds_read_b128 v[232:235], v207 offset:56320
	global_load_lds_dwordx4 v[236:237], off
	v_lshl_add_u64 v[236:237], v[242:243], 0, s[42:43]
	s_add_i32 m0, s46, 0x2000
	s_add_i32 s46, s49, s80
	global_load_lds_dwordx4 v[236:237], off
	v_lshl_add_u64 v[236:237], v[244:245], 0, s[42:43]
	s_mov_b32 m0, s46
	s_nop 0
	global_load_lds_dwordx4 v[236:237], off
	v_lshl_add_u64 v[236:237], v[246:247], 0, s[42:43]
	s_add_i32 m0, s46, 0x2000
	s_nop 0
	global_load_lds_dwordx4 v[236:237], off
	v_lshl_add_u64 v[236:237], v[248:249], 0, s[42:43]
	s_mov_b32 m0, s85
	s_nop 0
	global_load_lds_dwordx4 v[236:237], off
	v_lshl_add_u64 v[236:237], v[250:251], 0, s[42:43]
	s_mov_b32 m0, s86
	s_nop 0
	global_load_lds_dwordx4 v[236:237], off
	s_waitcnt vmcnt(8)
	s_waitcnt lgkmcnt(0)
	s_setprio 1
	s_waitcnt lgkmcnt(0)
	v_mfma_f32_16x16x32_bf16 v[62:65], v[130:133], v[186:189], v[62:65]
	v_mfma_f32_16x16x32_bf16 v[58:61], v[138:141], v[186:189], v[58:61]
	v_mfma_f32_16x16x32_bf16 v[54:57], v[130:133], v[212:215], v[54:57]
	v_mfma_f32_16x16x32_bf16 v[50:53], v[138:141], v[212:215], v[50:53]
	s_barrier
	v_mfma_f32_16x16x32_bf16 v[46:49], v[130:133], v[220:223], v[46:49]
	v_mfma_f32_16x16x32_bf16 v[42:45], v[138:141], v[220:223], v[42:45]
	v_mfma_f32_16x16x32_bf16 v[38:41], v[130:133], v[228:231], v[38:41]
	v_mfma_f32_16x16x32_bf16 v[34:37], v[138:141], v[228:231], v[34:37]
	v_mfma_f32_16x16x32_bf16 v[62:65], v[134:137], v[208:211], v[62:65]
	v_mfma_f32_16x16x32_bf16 v[58:61], v[142:145], v[208:211], v[58:61]
	v_mfma_f32_16x16x32_bf16 v[54:57], v[134:137], v[216:219], v[54:57]
	v_mfma_f32_16x16x32_bf16 v[50:53], v[142:145], v[216:219], v[50:53]
	v_mfma_f32_16x16x32_bf16 v[46:49], v[134:137], v[224:227], v[46:49]
	v_mfma_f32_16x16x32_bf16 v[42:45], v[142:145], v[224:227], v[42:45]
	v_mfma_f32_16x16x32_bf16 v[38:41], v[134:137], v[232:235], v[38:41]
	v_mfma_f32_16x16x32_bf16 v[34:37], v[142:145], v[232:235], v[34:37]
	v_mfma_f32_16x16x32_bf16 v[30:33], v[146:149], v[186:189], v[30:33]
	v_mfma_f32_16x16x32_bf16 v[26:29], v[178:181], v[186:189], v[26:29]
	v_mfma_f32_16x16x32_bf16 v[22:25], v[146:149], v[212:215], v[22:25]
	v_mfma_f32_16x16x32_bf16 v[18:21], v[178:181], v[212:215], v[18:21]
	v_mfma_f32_16x16x32_bf16 v[14:17], v[146:149], v[220:223], v[14:17]
	v_mfma_f32_16x16x32_bf16 v[10:13], v[178:181], v[220:223], v[10:13]
	v_mfma_f32_16x16x32_bf16 v[6:9], v[146:149], v[228:231], v[6:9]
	v_mfma_f32_16x16x32_bf16 v[2:5], v[178:181], v[228:231], v[2:5]
	v_mfma_f32_16x16x32_bf16 v[30:33], v[150:153], v[208:211], v[30:33]
	v_mfma_f32_16x16x32_bf16 v[26:29], v[182:185], v[208:211], v[26:29]
	v_mfma_f32_16x16x32_bf16 v[22:25], v[150:153], v[216:219], v[22:25]
	v_mfma_f32_16x16x32_bf16 v[18:21], v[182:185], v[216:219], v[18:21]
	v_mfma_f32_16x16x32_bf16 v[14:17], v[150:153], v[224:227], v[14:17]
	v_mfma_f32_16x16x32_bf16 v[10:13], v[182:185], v[224:227], v[10:13]
	v_mfma_f32_16x16x32_bf16 v[6:9], v[150:153], v[232:235], v[6:9]
	v_mfma_f32_16x16x32_bf16 v[2:5], v[182:185], v[232:235], v[2:5]
	s_barrier
	s_setprio 0
	s_add_u32 s72, s72, 0x100
	s_addc_u32 s73, s73, 0
	s_add_u32 s91, s91, 0x100
	s_addc_u32 s92, s92, 0
	s_cmp_ge_u32 s93, s84
	s_mov_b32 s60, s93
	s_cbranch_scc0 .LBB0_819
	s_and_b64 vcc, exec, s[18:19]
	s_cbranch_vccz .LBB0_822
	s_barrier

.LBB0_903:
	s_add_u32 s46, s66, 0xfff80080
	s_addc_u32 s47, s67, -1
	s_add_i32 s48, 0, 0x10000
	s_cmp_eq_u32 s84, 28
	s_cselect_b32 s69, s17, s47
	s_cselect_b32 s68, s64, s46
	s_cselect_b32 s61, s13, s83
	s_cselect_b32 s60, s81, s82
	s_add_i32 s49, 0, 0x14000
	v_add_u32_e32 v142, s48, v186
	v_add_u32_e32 v164, s49, v186
	ds_read_b128 v[130:133], v142
	ds_read_b128 v[134:137], v142 offset:1024
	ds_read_b128 v[138:141], v142 offset:2048
	ds_read_b128 v[142:145], v142 offset:3072
	ds_read_b128 v[146:149], v164
	ds_read_b128 v[160:163], v164 offset:1024
	ds_read_b128 v[178:181], v164 offset:2048
	ds_read_b128 v[182:185], v164 offset:3072
	v_lshl_add_u64 v[164:165], s[66:67], 0, v[156:157]
	s_add_i32 m0, s74, 0xc000
	ds_read_b128 v[206:209], v188
	ds_read_b128 v[210:213], v188 offset:1024
	ds_read_b128 v[214:217], v188 offset:2048
	ds_read_b128 v[218:221], v188 offset:3072
	ds_read_b128 v[222:225], v188 offset:4096
	ds_read_b128 v[226:229], v188 offset:5120
	ds_read_b128 v[230:233], v188 offset:6144
	ds_read_b128 v[234:237], v188 offset:7168
	global_load_lds_dwordx4 v[164:165], off
	v_lshl_add_u64 v[164:165], s[66:67], 0, v[158:159]
	s_add_i32 m0, s74, 0xe000
	s_nop 0
	global_load_lds_dwordx4 v[164:165], off
	s_waitcnt vmcnt(8)
	s_waitcnt lgkmcnt(0)
	s_setprio 1
	s_waitcnt lgkmcnt(0)
	v_mfma_f32_16x16x32_bf16 v[126:129], v[130:133], v[206:209], v[126:129]
	v_mfma_f32_16x16x32_bf16 v[122:125], v[138:141], v[206:209], v[122:125]
	v_mfma_f32_16x16x32_bf16 v[118:121], v[130:133], v[214:217], v[118:121]
	v_mfma_f32_16x16x32_bf16 v[110:113], v[138:141], v[214:217], v[110:113]
	s_barrier
	v_mfma_f32_16x16x32_bf16 v[94:97], v[130:133], v[222:225], v[94:97]
	v_mfma_f32_16x16x32_bf16 v[90:93], v[138:141], v[222:225], v[90:93]
	v_mfma_f32_16x16x32_bf16 v[82:85], v[130:133], v[230:233], v[82:85]
	v_mfma_f32_16x16x32_bf16 v[74:77], v[138:141], v[230:233], v[74:77]
	v_mfma_f32_16x16x32_bf16 v[126:129], v[134:137], v[210:213], v[126:129]
	v_mfma_f32_16x16x32_bf16 v[122:125], v[142:145], v[210:213], v[122:125]
	v_mfma_f32_16x16x32_bf16 v[118:121], v[134:137], v[218:221], v[118:121]
	v_mfma_f32_16x16x32_bf16 v[110:113], v[142:145], v[218:221], v[110:113]
	v_mfma_f32_16x16x32_bf16 v[94:97], v[134:137], v[226:229], v[94:97]
	v_mfma_f32_16x16x32_bf16 v[90:93], v[142:145], v[226:229], v[90:93]
	v_mfma_f32_16x16x32_bf16 v[82:85], v[134:137], v[234:237], v[82:85]
	v_mfma_f32_16x16x32_bf16 v[74:77], v[142:145], v[234:237], v[74:77]
	v_mfma_f32_16x16x32_bf16 v[114:117], v[146:149], v[206:209], v[114:117]
	v_mfma_f32_16x16x32_bf16 v[106:109], v[178:181], v[206:209], v[106:109]
	v_mfma_f32_16x16x32_bf16 v[102:105], v[146:149], v[214:217], v[102:105]
	v_mfma_f32_16x16x32_bf16 v[98:101], v[178:181], v[214:217], v[98:101]
	v_mfma_f32_16x16x32_bf16 v[86:89], v[146:149], v[222:225], v[86:89]
	v_mfma_f32_16x16x32_bf16 v[78:81], v[178:181], v[222:225], v[78:81]
	v_mfma_f32_16x16x32_bf16 v[70:73], v[146:149], v[230:233], v[70:73]
	v_mfma_f32_16x16x32_bf16 v[66:69], v[178:181], v[230:233], v[66:69]
	v_mfma_f32_16x16x32_bf16 v[114:117], v[160:163], v[210:213], v[114:117]
	v_mfma_f32_16x16x32_bf16 v[106:109], v[182:185], v[210:213], v[106:109]
	v_mfma_f32_16x16x32_bf16 v[102:105], v[160:163], v[218:221], v[102:105]
	v_mfma_f32_16x16x32_bf16 v[98:101], v[182:185], v[218:221], v[98:101]
	v_mfma_f32_16x16x32_bf16 v[86:89], v[160:163], v[226:229], v[86:89]
	v_mfma_f32_16x16x32_bf16 v[78:81], v[182:185], v[226:229], v[78:81]
	v_mfma_f32_16x16x32_bf16 v[70:73], v[160:163], v[234:237], v[70:73]
	v_mfma_f32_16x16x32_bf16 v[66:69], v[182:185], v[234:237], v[66:69]
	s_barrier
	s_setprio 0
	s_add_i32 s46, s48, s73
	v_lshl_add_u64 v[164:165], s[60:61], 0, v[166:167]
	s_mov_b32 m0, s46
	ds_read_b128 v[206:209], v188 offset:16384
	ds_read_b128 v[210:213], v188 offset:17408
	ds_read_b128 v[214:217], v188 offset:18432
	ds_read_b128 v[218:221], v188 offset:19456
	ds_read_b128 v[222:225], v188 offset:20480
	ds_read_b128 v[226:229], v188 offset:21504
	ds_read_b128 v[230:233], v188 offset:22528
	ds_read_b128 v[234:237], v188 offset:23552
	global_load_lds_dwordx4 v[164:165], off
	s_add_i32 m0, s46, 0x2000
	s_add_u32 s46, s60, 0x80000
	v_lshl_add_u64 v[242:243], s[60:61], 0, v[154:155]
	s_addc_u32 s47, s61, 0
	s_add_i32 s48, s49, s73
	global_load_lds_dwordx4 v[242:243], off
	v_lshl_add_u64 v[244:245], s[46:47], 0, v[166:167]
	s_mov_b32 m0, s48
	v_lshl_add_u64 v[246:247], s[68:69], 0, v[152:153]
	global_load_lds_dwordx4 v[244:245], off
	v_lshl_add_u64 v[244:245], s[46:47], 0, v[154:155]
	s_add_i32 m0, s48, 0x2000
	s_nop 0
	global_load_lds_dwordx4 v[244:245], off
	v_lshl_add_u64 v[244:245], s[68:69], 0, v[150:151]
	s_mov_b32 m0, s74
	s_nop 0
	global_load_lds_dwordx4 v[244:245], off
	s_mov_b32 m0, s75
	s_nop 0
	global_load_lds_dwordx4 v[246:247], off
	s_waitcnt vmcnt(8)
	s_waitcnt lgkmcnt(0)
	s_setprio 1
	s_waitcnt lgkmcnt(0)
	v_mfma_f32_16x16x32_bf16 v[62:65], v[130:133], v[206:209], v[62:65]
	v_mfma_f32_16x16x32_bf16 v[58:61], v[138:141], v[206:209], v[58:61]
	v_mfma_f32_16x16x32_bf16 v[50:53], v[130:133], v[214:217], v[50:53]
	v_mfma_f32_16x16x32_bf16 v[42:45], v[138:141], v[214:217], v[42:45]
	s_barrier
	v_mfma_f32_16x16x32_bf16 v[34:37], v[130:133], v[222:225], v[34:37]
	v_mfma_f32_16x16x32_bf16 v[26:29], v[138:141], v[222:225], v[26:29]
	v_mfma_f32_16x16x32_bf16 v[18:21], v[130:133], v[230:233], v[18:21]
	v_mfma_f32_16x16x32_bf16 v[10:13], v[138:141], v[230:233], v[10:13]
	v_mfma_f32_16x16x32_bf16 v[62:65], v[134:137], v[210:213], v[62:65]
	v_mfma_f32_16x16x32_bf16 v[58:61], v[142:145], v[210:213], v[58:61]
	v_mfma_f32_16x16x32_bf16 v[50:53], v[134:137], v[218:221], v[50:53]
	v_mfma_f32_16x16x32_bf16 v[42:45], v[142:145], v[218:221], v[42:45]
	v_mfma_f32_16x16x32_bf16 v[34:37], v[134:137], v[226:229], v[34:37]
	v_mfma_f32_16x16x32_bf16 v[26:29], v[142:145], v[226:229], v[26:29]
	v_mfma_f32_16x16x32_bf16 v[18:21], v[134:137], v[234:237], v[18:21]
	v_mfma_f32_16x16x32_bf16 v[10:13], v[142:145], v[234:237], v[10:13]
	v_mfma_f32_16x16x32_bf16 v[54:57], v[146:149], v[206:209], v[54:57]
	v_mfma_f32_16x16x32_bf16 v[46:49], v[178:181], v[206:209], v[46:49]
	v_mfma_f32_16x16x32_bf16 v[38:41], v[146:149], v[214:217], v[38:41]
	v_mfma_f32_16x16x32_bf16 v[30:33], v[178:181], v[214:217], v[30:33]
	v_mfma_f32_16x16x32_bf16 v[22:25], v[146:149], v[222:225], v[22:25]
	v_mfma_f32_16x16x32_bf16 v[14:17], v[178:181], v[222:225], v[14:17]
	v_mfma_f32_16x16x32_bf16 v[6:9], v[146:149], v[230:233], v[6:9]
	v_mfma_f32_16x16x32_bf16 v[2:5], v[178:181], v[230:233], v[2:5]
	v_mfma_f32_16x16x32_bf16 v[54:57], v[160:163], v[210:213], v[54:57]
	v_mfma_f32_16x16x32_bf16 v[46:49], v[182:185], v[210:213], v[46:49]
	v_mfma_f32_16x16x32_bf16 v[38:41], v[160:163], v[218:221], v[38:41]
	v_mfma_f32_16x16x32_bf16 v[30:33], v[182:185], v[218:221], v[30:33]
	v_mfma_f32_16x16x32_bf16 v[22:25], v[160:163], v[226:229], v[22:25]
	v_mfma_f32_16x16x32_bf16 v[14:17], v[182:185], v[226:229], v[14:17]
	v_mfma_f32_16x16x32_bf16 v[6:9], v[160:163], v[234:237], v[6:9]
	v_mfma_f32_16x16x32_bf16 v[2:5], v[182:185], v[234:237], v[2:5]
	s_barrier
	s_setprio 0
	s_add_i32 s48, 0, 0x18000
	s_add_i32 s49, 0, 0x1c000
	v_add_u32_e32 v142, s48, v186
	v_add_u32_e32 v182, s49, v186
	ds_read_b128 v[130:133], v142
	ds_read_b128 v[134:137], v142 offset:1024
	ds_read_b128 v[138:141], v142 offset:2048
	ds_read_b128 v[142:145], v142 offset:3072
	ds_read_b128 v[146:149], v182
	ds_read_b128 v[160:163], v182 offset:1024
	ds_read_b128 v[178:181], v182 offset:2048
	ds_read_b128 v[182:185], v182 offset:3072
	s_add_u32 s46, s68, 0x80000
	s_addc_u32 s47, s69, 0
	s_mov_b32 m0, s76
	v_lshl_add_u64 v[248:249], s[46:47], 0, v[150:151]
	ds_read_b128 v[206:209], v188 offset:32768
	ds_read_b128 v[210:213], v188 offset:33792
	ds_read_b128 v[214:217], v188 offset:34816
	ds_read_b128 v[218:221], v188 offset:35840
	ds_read_b128 v[222:225], v188 offset:36864
	ds_read_b128 v[226:229], v188 offset:37888
	ds_read_b128 v[230:233], v188 offset:38912
	ds_read_b128 v[234:237], v188 offset:39936
	global_load_lds_dwordx4 v[248:249], off
	v_lshl_add_u64 v[248:249], s[46:47], 0, v[152:153]
	s_mov_b32 m0, s77
	s_nop 0
	global_load_lds_dwordx4 v[248:249], off
	s_waitcnt vmcnt(8)
	s_waitcnt lgkmcnt(0)
	s_setprio 1
	s_waitcnt lgkmcnt(0)
	v_mfma_f32_16x16x32_bf16 v[126:129], v[130:133], v[206:209], v[126:129]
	v_mfma_f32_16x16x32_bf16 v[122:125], v[138:141], v[206:209], v[122:125]
	v_mfma_f32_16x16x32_bf16 v[118:121], v[130:133], v[214:217], v[118:121]
	v_mfma_f32_16x16x32_bf16 v[110:113], v[138:141], v[214:217], v[110:113]
	s_barrier
	v_mfma_f32_16x16x32_bf16 v[94:97], v[130:133], v[222:225], v[94:97]
	v_mfma_f32_16x16x32_bf16 v[90:93], v[138:141], v[222:225], v[90:93]
	v_mfma_f32_16x16x32_bf16 v[82:85], v[130:133], v[230:233], v[82:85]
	v_mfma_f32_16x16x32_bf16 v[74:77], v[138:141], v[230:233], v[74:77]
	v_mfma_f32_16x16x32_bf16 v[126:129], v[134:137], v[210:213], v[126:129]
	v_mfma_f32_16x16x32_bf16 v[122:125], v[142:145], v[210:213], v[122:125]
	v_mfma_f32_16x16x32_bf16 v[118:121], v[134:137], v[218:221], v[118:121]
	v_mfma_f32_16x16x32_bf16 v[110:113], v[142:145], v[218:221], v[110:113]
	v_mfma_f32_16x16x32_bf16 v[94:97], v[134:137], v[226:229], v[94:97]
	v_mfma_f32_16x16x32_bf16 v[90:93], v[142:145], v[226:229], v[90:93]
	v_mfma_f32_16x16x32_bf16 v[82:85], v[134:137], v[234:237], v[82:85]
	v_mfma_f32_16x16x32_bf16 v[74:77], v[142:145], v[234:237], v[74:77]
	v_mfma_f32_16x16x32_bf16 v[114:117], v[146:149], v[206:209], v[114:117]
	v_mfma_f32_16x16x32_bf16 v[106:109], v[178:181], v[206:209], v[106:109]
	v_mfma_f32_16x16x32_bf16 v[102:105], v[146:149], v[214:217], v[102:105]
	v_mfma_f32_16x16x32_bf16 v[98:101], v[178:181], v[214:217], v[98:101]
	v_mfma_f32_16x16x32_bf16 v[86:89], v[146:149], v[222:225], v[86:89]
	v_mfma_f32_16x16x32_bf16 v[78:81], v[178:181], v[222:225], v[78:81]
	v_mfma_f32_16x16x32_bf16 v[70:73], v[146:149], v[230:233], v[70:73]
	v_mfma_f32_16x16x32_bf16 v[66:69], v[178:181], v[230:233], v[66:69]
	v_mfma_f32_16x16x32_bf16 v[114:117], v[160:163], v[210:213], v[114:117]
	v_mfma_f32_16x16x32_bf16 v[106:109], v[182:185], v[210:213], v[106:109]
	v_mfma_f32_16x16x32_bf16 v[102:105], v[160:163], v[218:221], v[102:105]
	v_mfma_f32_16x16x32_bf16 v[98:101], v[182:185], v[218:221], v[98:101]
	v_mfma_f32_16x16x32_bf16 v[86:89], v[160:163], v[226:229], v[86:89]
	v_mfma_f32_16x16x32_bf16 v[78:81], v[182:185], v[226:229], v[78:81]
	v_mfma_f32_16x16x32_bf16 v[70:73], v[160:163], v[234:237], v[70:73]
	v_mfma_f32_16x16x32_bf16 v[66:69], v[182:185], v[234:237], v[66:69]
	s_barrier
	s_setprio 0
	s_add_i32 s46, s48, s73
	v_lshl_add_u64 v[164:165], v[164:165], 0, s[42:43]
	s_mov_b32 m0, s46
	ds_read_b128 v[206:209], v188 offset:49152
	ds_read_b128 v[210:213], v188 offset:50176
	ds_read_b128 v[214:217], v188 offset:51200
	ds_read_b128 v[218:221], v188 offset:52224
	ds_read_b128 v[222:225], v188 offset:53248
	ds_read_b128 v[226:229], v188 offset:54272
	ds_read_b128 v[230:233], v188 offset:55296
	ds_read_b128 v[234:237], v188 offset:56320
	global_load_lds_dwordx4 v[164:165], off
	s_add_i32 m0, s46, 0x2000
	s_add_u32 s46, s60, 0x80080
	v_lshl_add_u64 v[164:165], v[242:243], 0, s[42:43]
	s_addc_u32 s47, s61, 0
	s_add_i32 s48, s49, s73
	global_load_lds_dwordx4 v[164:165], off
	v_lshl_add_u64 v[164:165], s[46:47], 0, v[166:167]
	s_mov_b32 m0, s48
	s_nop 0
	global_load_lds_dwordx4 v[164:165], off
	v_lshl_add_u64 v[164:165], s[46:47], 0, v[154:155]
	s_add_i32 m0, s48, 0x2000
	s_nop 0
	global_load_lds_dwordx4 v[164:165], off
	v_lshl_add_u64 v[164:165], v[244:245], 0, s[42:43]
	s_mov_b32 m0, s78
	s_nop 0
	global_load_lds_dwordx4 v[164:165], off
	v_lshl_add_u64 v[164:165], v[246:247], 0, s[42:43]
	s_mov_b32 m0, s79
	s_nop 0
	global_load_lds_dwordx4 v[164:165], off
	s_waitcnt vmcnt(8)
	s_waitcnt lgkmcnt(0)
	s_setprio 1
	s_waitcnt lgkmcnt(0)
	v_mfma_f32_16x16x32_bf16 v[62:65], v[130:133], v[206:209], v[62:65]
	v_mfma_f32_16x16x32_bf16 v[58:61], v[138:141], v[206:209], v[58:61]
	v_mfma_f32_16x16x32_bf16 v[50:53], v[130:133], v[214:217], v[50:53]
	v_mfma_f32_16x16x32_bf16 v[42:45], v[138:141], v[214:217], v[42:45]
	s_barrier
	v_mfma_f32_16x16x32_bf16 v[34:37], v[130:133], v[222:225], v[34:37]
	v_mfma_f32_16x16x32_bf16 v[26:29], v[138:141], v[222:225], v[26:29]
	v_mfma_f32_16x16x32_bf16 v[18:21], v[130:133], v[230:233], v[18:21]
	v_mfma_f32_16x16x32_bf16 v[10:13], v[138:141], v[230:233], v[10:13]
	v_mfma_f32_16x16x32_bf16 v[62:65], v[134:137], v[210:213], v[62:65]
	v_mfma_f32_16x16x32_bf16 v[58:61], v[142:145], v[210:213], v[58:61]
	v_mfma_f32_16x16x32_bf16 v[50:53], v[134:137], v[218:221], v[50:53]
	v_mfma_f32_16x16x32_bf16 v[42:45], v[142:145], v[218:221], v[42:45]
	v_mfma_f32_16x16x32_bf16 v[34:37], v[134:137], v[226:229], v[34:37]
	v_mfma_f32_16x16x32_bf16 v[26:29], v[142:145], v[226:229], v[26:29]
	v_mfma_f32_16x16x32_bf16 v[18:21], v[134:137], v[234:237], v[18:21]
	v_mfma_f32_16x16x32_bf16 v[10:13], v[142:145], v[234:237], v[10:13]
	v_mfma_f32_16x16x32_bf16 v[54:57], v[146:149], v[206:209], v[54:57]
	v_mfma_f32_16x16x32_bf16 v[46:49], v[178:181], v[206:209], v[46:49]
	v_mfma_f32_16x16x32_bf16 v[38:41], v[146:149], v[214:217], v[38:41]
	v_mfma_f32_16x16x32_bf16 v[30:33], v[178:181], v[214:217], v[30:33]
	v_mfma_f32_16x16x32_bf16 v[22:25], v[146:149], v[222:225], v[22:25]
	v_mfma_f32_16x16x32_bf16 v[14:17], v[178:181], v[222:225], v[14:17]
	v_mfma_f32_16x16x32_bf16 v[6:9], v[146:149], v[230:233], v[6:9]
	v_mfma_f32_16x16x32_bf16 v[2:5], v[178:181], v[230:233], v[2:5]
	v_mfma_f32_16x16x32_bf16 v[54:57], v[160:163], v[210:213], v[54:57]
	v_mfma_f32_16x16x32_bf16 v[46:49], v[182:185], v[210:213], v[46:49]
	v_mfma_f32_16x16x32_bf16 v[38:41], v[160:163], v[218:221], v[38:41]
	v_mfma_f32_16x16x32_bf16 v[30:33], v[182:185], v[218:221], v[30:33]
	v_mfma_f32_16x16x32_bf16 v[22:25], v[160:163], v[226:229], v[22:25]
	v_mfma_f32_16x16x32_bf16 v[14:17], v[182:185], v[226:229], v[14:17]
	v_mfma_f32_16x16x32_bf16 v[6:9], v[160:163], v[234:237], v[6:9]
	v_mfma_f32_16x16x32_bf16 v[2:5], v[182:185], v[234:237], v[2:5]
	s_barrier
	s_setprio 0
	s_add_i32 s84, s84, 2
	s_add_u32 s66, s66, 0x100
	s_addc_u32 s67, s67, 0
	s_add_u32 s82, s82, 0x100
	s_addc_u32 s83, s83, 0
	s_cmp_gt_u32 s84, 29
	s_cbranch_scc0 .LBB0_903
	s_and_b64 vcc, exec, s[10:11]
	s_cbranch_vccz .LBB0_906
	s_barrier

.LBB0_1035:
	s_add_u32 s46, s64, 0xfff80080
	s_addc_u32 s47, s65, -1
	s_add_i32 s48, 0, 0x10000
	s_cmp_eq_u32 s84, 28
	s_cselect_b32 s67, s17, s47
	s_cselect_b32 s66, s80, s46
	v_add_u32_e32 v140, s48, v142
	s_cselect_b32 s61, s13, s83
	s_cselect_b32 s60, s81, s82
	s_add_i32 s49, 0, 0x14000
	ds_read_b128 v[146:149], v140
	ds_read_b128 v[150:153], v140 offset:1024
	ds_read_b128 v[154:157], v140 offset:2048
	ds_read_b128 v[158:161], v140 offset:3072
	v_add_u32_e32 v140, s49, v142
	ds_read_b128 v[162:165], v140
	ds_read_b128 v[178:181], v140 offset:1024
	ds_read_b128 v[182:185], v140 offset:2048
	ds_read_b128 v[186:189], v140 offset:3072
	v_lshl_add_u64 v[140:141], s[64:65], 0, v[136:137]
	s_add_i32 m0, s23, 0xc000
	ds_read_b128 v[206:209], v144
	ds_read_b128 v[210:213], v144 offset:1024
	ds_read_b128 v[214:217], v144 offset:2048
	ds_read_b128 v[218:221], v144 offset:3072
	ds_read_b128 v[222:225], v144 offset:4096
	ds_read_b128 v[226:229], v144 offset:5120
	ds_read_b128 v[230:233], v144 offset:6144
	ds_read_b128 v[234:237], v144 offset:7168
	global_load_lds_dwordx4 v[140:141], off
	v_lshl_add_u64 v[140:141], s[64:65], 0, v[138:139]
	s_add_i32 m0, s23, 0xe000
	s_nop 0
	global_load_lds_dwordx4 v[140:141], off
	s_waitcnt vmcnt(8)
	s_waitcnt lgkmcnt(0)
	s_setprio 1
	s_waitcnt lgkmcnt(0)
	v_mfma_f32_16x16x32_bf16 v[126:129], v[146:149], v[206:209], v[126:129]
	v_mfma_f32_16x16x32_bf16 v[122:125], v[154:157], v[206:209], v[122:125]
	v_mfma_f32_16x16x32_bf16 v[110:113], v[146:149], v[214:217], v[110:113]
	v_mfma_f32_16x16x32_bf16 v[106:109], v[154:157], v[214:217], v[106:109]
	s_barrier
	v_mfma_f32_16x16x32_bf16 v[94:97], v[146:149], v[222:225], v[94:97]
	v_mfma_f32_16x16x32_bf16 v[90:93], v[154:157], v[222:225], v[90:93]
	v_mfma_f32_16x16x32_bf16 v[78:81], v[146:149], v[230:233], v[78:81]
	v_mfma_f32_16x16x32_bf16 v[74:77], v[154:157], v[230:233], v[74:77]
	v_mfma_f32_16x16x32_bf16 v[126:129], v[150:153], v[210:213], v[126:129]
	v_mfma_f32_16x16x32_bf16 v[122:125], v[158:161], v[210:213], v[122:125]
	v_mfma_f32_16x16x32_bf16 v[110:113], v[150:153], v[218:221], v[110:113]
	v_mfma_f32_16x16x32_bf16 v[106:109], v[158:161], v[218:221], v[106:109]
	v_mfma_f32_16x16x32_bf16 v[94:97], v[150:153], v[226:229], v[94:97]
	v_mfma_f32_16x16x32_bf16 v[90:93], v[158:161], v[226:229], v[90:93]
	v_mfma_f32_16x16x32_bf16 v[78:81], v[150:153], v[234:237], v[78:81]
	v_mfma_f32_16x16x32_bf16 v[74:77], v[158:161], v[234:237], v[74:77]
	v_mfma_f32_16x16x32_bf16 v[118:121], v[162:165], v[206:209], v[118:121]
	v_mfma_f32_16x16x32_bf16 v[114:117], v[182:185], v[206:209], v[114:117]
	v_mfma_f32_16x16x32_bf16 v[102:105], v[162:165], v[214:217], v[102:105]
	v_mfma_f32_16x16x32_bf16 v[98:101], v[182:185], v[214:217], v[98:101]
	v_mfma_f32_16x16x32_bf16 v[86:89], v[162:165], v[222:225], v[86:89]
	v_mfma_f32_16x16x32_bf16 v[82:85], v[182:185], v[222:225], v[82:85]
	v_mfma_f32_16x16x32_bf16 v[70:73], v[162:165], v[230:233], v[70:73]
	v_mfma_f32_16x16x32_bf16 v[66:69], v[182:185], v[230:233], v[66:69]
	v_mfma_f32_16x16x32_bf16 v[118:121], v[178:181], v[210:213], v[118:121]
	v_mfma_f32_16x16x32_bf16 v[114:117], v[186:189], v[210:213], v[114:117]
	v_mfma_f32_16x16x32_bf16 v[102:105], v[178:181], v[218:221], v[102:105]
	v_mfma_f32_16x16x32_bf16 v[98:101], v[186:189], v[218:221], v[98:101]
	v_mfma_f32_16x16x32_bf16 v[86:89], v[178:181], v[226:229], v[86:89]
	v_mfma_f32_16x16x32_bf16 v[82:85], v[186:189], v[226:229], v[82:85]
	v_mfma_f32_16x16x32_bf16 v[70:73], v[178:181], v[234:237], v[70:73]
	v_mfma_f32_16x16x32_bf16 v[66:69], v[186:189], v[234:237], v[66:69]
	s_barrier
	s_setprio 0
	s_add_i32 s46, s48, s72
	v_lshl_add_u64 v[140:141], s[60:61], 0, v[166:167]
	s_mov_b32 m0, s46
	ds_read_b128 v[206:209], v144 offset:16384
	ds_read_b128 v[210:213], v144 offset:17408
	ds_read_b128 v[214:217], v144 offset:18432
	ds_read_b128 v[218:221], v144 offset:19456
	ds_read_b128 v[222:225], v144 offset:20480
	ds_read_b128 v[226:229], v144 offset:21504
	ds_read_b128 v[230:233], v144 offset:22528
	ds_read_b128 v[234:237], v144 offset:23552
	global_load_lds_dwordx4 v[140:141], off
	s_add_i32 m0, s46, 0x2000
	s_add_u32 s46, s60, 0x80000
	v_lshl_add_u64 v[242:243], s[60:61], 0, v[134:135]
	s_addc_u32 s47, s61, 0
	s_add_i32 s48, s49, s72
	global_load_lds_dwordx4 v[242:243], off
	v_lshl_add_u64 v[244:245], s[46:47], 0, v[166:167]
	s_mov_b32 m0, s48
	v_lshl_add_u64 v[246:247], s[66:67], 0, v[132:133]
	global_load_lds_dwordx4 v[244:245], off
	v_lshl_add_u64 v[244:245], s[46:47], 0, v[134:135]
	s_add_i32 m0, s48, 0x2000
	s_nop 0
	global_load_lds_dwordx4 v[244:245], off
	v_lshl_add_u64 v[244:245], s[66:67], 0, v[130:131]
	s_mov_b32 m0, s23
	s_nop 0
	global_load_lds_dwordx4 v[244:245], off
	s_mov_b32 m0, s73
	s_nop 0
	global_load_lds_dwordx4 v[246:247], off
	s_waitcnt vmcnt(8)
	s_waitcnt lgkmcnt(0)
	s_setprio 1
	s_waitcnt lgkmcnt(0)
	v_mfma_f32_16x16x32_bf16 v[62:65], v[146:149], v[206:209], v[62:65]
	v_mfma_f32_16x16x32_bf16 v[58:61], v[154:157], v[206:209], v[58:61]
	v_mfma_f32_16x16x32_bf16 v[46:49], v[146:149], v[214:217], v[46:49]
	v_mfma_f32_16x16x32_bf16 v[42:45], v[154:157], v[214:217], v[42:45]
	s_barrier
	v_mfma_f32_16x16x32_bf16 v[30:33], v[146:149], v[222:225], v[30:33]
	v_mfma_f32_16x16x32_bf16 v[26:29], v[154:157], v[222:225], v[26:29]
	v_mfma_f32_16x16x32_bf16 v[14:17], v[146:149], v[230:233], v[14:17]
	v_mfma_f32_16x16x32_bf16 v[10:13], v[154:157], v[230:233], v[10:13]
	v_mfma_f32_16x16x32_bf16 v[62:65], v[150:153], v[210:213], v[62:65]
	v_mfma_f32_16x16x32_bf16 v[58:61], v[158:161], v[210:213], v[58:61]
	v_mfma_f32_16x16x32_bf16 v[46:49], v[150:153], v[218:221], v[46:49]
	v_mfma_f32_16x16x32_bf16 v[42:45], v[158:161], v[218:221], v[42:45]
	v_mfma_f32_16x16x32_bf16 v[30:33], v[150:153], v[226:229], v[30:33]
	v_mfma_f32_16x16x32_bf16 v[26:29], v[158:161], v[226:229], v[26:29]
	v_mfma_f32_16x16x32_bf16 v[14:17], v[150:153], v[234:237], v[14:17]
	v_mfma_f32_16x16x32_bf16 v[10:13], v[158:161], v[234:237], v[10:13]
	v_mfma_f32_16x16x32_bf16 v[54:57], v[162:165], v[206:209], v[54:57]
	v_mfma_f32_16x16x32_bf16 v[50:53], v[182:185], v[206:209], v[50:53]
	v_mfma_f32_16x16x32_bf16 v[38:41], v[162:165], v[214:217], v[38:41]
	v_mfma_f32_16x16x32_bf16 v[34:37], v[182:185], v[214:217], v[34:37]
	v_mfma_f32_16x16x32_bf16 v[22:25], v[162:165], v[222:225], v[22:25]
	v_mfma_f32_16x16x32_bf16 v[18:21], v[182:185], v[222:225], v[18:21]
	v_mfma_f32_16x16x32_bf16 v[6:9], v[162:165], v[230:233], v[6:9]
	v_mfma_f32_16x16x32_bf16 v[2:5], v[182:185], v[230:233], v[2:5]
	v_mfma_f32_16x16x32_bf16 v[54:57], v[178:181], v[210:213], v[54:57]
	v_mfma_f32_16x16x32_bf16 v[50:53], v[186:189], v[210:213], v[50:53]
	v_mfma_f32_16x16x32_bf16 v[38:41], v[178:181], v[218:221], v[38:41]
	v_mfma_f32_16x16x32_bf16 v[34:37], v[186:189], v[218:221], v[34:37]
	v_mfma_f32_16x16x32_bf16 v[22:25], v[178:181], v[226:229], v[22:25]
	v_mfma_f32_16x16x32_bf16 v[18:21], v[186:189], v[226:229], v[18:21]
	v_mfma_f32_16x16x32_bf16 v[6:9], v[178:181], v[234:237], v[6:9]
	v_mfma_f32_16x16x32_bf16 v[2:5], v[186:189], v[234:237], v[2:5]
	s_barrier
	s_setprio 0
	s_add_i32 s48, 0, 0x18000
	v_add_u32_e32 v145, s48, v142
	s_add_i32 s49, 0, 0x1c000
	ds_read_b128 v[146:149], v145
	ds_read_b128 v[150:153], v145 offset:1024
	ds_read_b128 v[154:157], v145 offset:2048
	ds_read_b128 v[158:161], v145 offset:3072
	v_add_u32_e32 v145, s49, v142
	ds_read_b128 v[162:165], v145
	ds_read_b128 v[178:181], v145 offset:1024
	ds_read_b128 v[182:185], v145 offset:2048
	ds_read_b128 v[186:189], v145 offset:3072
	s_add_u32 s46, s66, 0x80000
	s_addc_u32 s47, s67, 0
	s_mov_b32 m0, s74
	v_lshl_add_u64 v[248:249], s[46:47], 0, v[130:131]
	ds_read_b128 v[206:209], v144 offset:32768
	ds_read_b128 v[210:213], v144 offset:33792
	ds_read_b128 v[214:217], v144 offset:34816
	ds_read_b128 v[218:221], v144 offset:35840
	ds_read_b128 v[222:225], v144 offset:36864
	ds_read_b128 v[226:229], v144 offset:37888
	ds_read_b128 v[230:233], v144 offset:38912
	ds_read_b128 v[234:237], v144 offset:39936
	global_load_lds_dwordx4 v[248:249], off
	v_lshl_add_u64 v[248:249], s[46:47], 0, v[132:133]
	s_mov_b32 m0, s75
	s_nop 0
	global_load_lds_dwordx4 v[248:249], off
	s_waitcnt vmcnt(8)
	s_waitcnt lgkmcnt(0)
	s_setprio 1
	s_waitcnt lgkmcnt(0)
	v_mfma_f32_16x16x32_bf16 v[126:129], v[146:149], v[206:209], v[126:129]
	v_mfma_f32_16x16x32_bf16 v[122:125], v[154:157], v[206:209], v[122:125]
	v_mfma_f32_16x16x32_bf16 v[110:113], v[146:149], v[214:217], v[110:113]
	v_mfma_f32_16x16x32_bf16 v[106:109], v[154:157], v[214:217], v[106:109]
	s_barrier
	v_mfma_f32_16x16x32_bf16 v[94:97], v[146:149], v[222:225], v[94:97]
	v_mfma_f32_16x16x32_bf16 v[90:93], v[154:157], v[222:225], v[90:93]
	v_mfma_f32_16x16x32_bf16 v[78:81], v[146:149], v[230:233], v[78:81]
	v_mfma_f32_16x16x32_bf16 v[74:77], v[154:157], v[230:233], v[74:77]
	v_mfma_f32_16x16x32_bf16 v[126:129], v[150:153], v[210:213], v[126:129]
	v_mfma_f32_16x16x32_bf16 v[122:125], v[158:161], v[210:213], v[122:125]
	v_mfma_f32_16x16x32_bf16 v[110:113], v[150:153], v[218:221], v[110:113]
	v_mfma_f32_16x16x32_bf16 v[106:109], v[158:161], v[218:221], v[106:109]
	v_mfma_f32_16x16x32_bf16 v[94:97], v[150:153], v[226:229], v[94:97]
	v_mfma_f32_16x16x32_bf16 v[90:93], v[158:161], v[226:229], v[90:93]
	v_mfma_f32_16x16x32_bf16 v[78:81], v[150:153], v[234:237], v[78:81]
	v_mfma_f32_16x16x32_bf16 v[74:77], v[158:161], v[234:237], v[74:77]
	v_mfma_f32_16x16x32_bf16 v[118:121], v[162:165], v[206:209], v[118:121]
	v_mfma_f32_16x16x32_bf16 v[114:117], v[182:185], v[206:209], v[114:117]
	v_mfma_f32_16x16x32_bf16 v[102:105], v[162:165], v[214:217], v[102:105]
	v_mfma_f32_16x16x32_bf16 v[98:101], v[182:185], v[214:217], v[98:101]
	v_mfma_f32_16x16x32_bf16 v[86:89], v[162:165], v[222:225], v[86:89]
	v_mfma_f32_16x16x32_bf16 v[82:85], v[182:185], v[222:225], v[82:85]
	v_mfma_f32_16x16x32_bf16 v[70:73], v[162:165], v[230:233], v[70:73]
	v_mfma_f32_16x16x32_bf16 v[66:69], v[182:185], v[230:233], v[66:69]
	v_mfma_f32_16x16x32_bf16 v[118:121], v[178:181], v[210:213], v[118:121]
	v_mfma_f32_16x16x32_bf16 v[114:117], v[186:189], v[210:213], v[114:117]
	v_mfma_f32_16x16x32_bf16 v[102:105], v[178:181], v[218:221], v[102:105]
	v_mfma_f32_16x16x32_bf16 v[98:101], v[186:189], v[218:221], v[98:101]
	v_mfma_f32_16x16x32_bf16 v[86:89], v[178:181], v[226:229], v[86:89]
	v_mfma_f32_16x16x32_bf16 v[82:85], v[186:189], v[226:229], v[82:85]
	v_mfma_f32_16x16x32_bf16 v[70:73], v[178:181], v[234:237], v[70:73]
	v_mfma_f32_16x16x32_bf16 v[66:69], v[186:189], v[234:237], v[66:69]
	s_barrier
	s_setprio 0
	s_add_i32 s46, s48, s72
	v_lshl_add_u64 v[140:141], v[140:141], 0, s[42:43]
	s_mov_b32 m0, s46
	ds_read_b128 v[206:209], v144 offset:49152
	ds_read_b128 v[210:213], v144 offset:50176
	ds_read_b128 v[214:217], v144 offset:51200
	ds_read_b128 v[218:221], v144 offset:52224
	ds_read_b128 v[222:225], v144 offset:53248
	ds_read_b128 v[226:229], v144 offset:54272
	ds_read_b128 v[230:233], v144 offset:55296
	ds_read_b128 v[234:237], v144 offset:56320
	global_load_lds_dwordx4 v[140:141], off
	s_add_i32 m0, s46, 0x2000
	s_add_u32 s46, s60, 0x80080
	v_lshl_add_u64 v[140:141], v[242:243], 0, s[42:43]
	s_addc_u32 s47, s61, 0
	s_add_i32 s48, s49, s72
	global_load_lds_dwordx4 v[140:141], off
	v_lshl_add_u64 v[140:141], s[46:47], 0, v[166:167]
	s_mov_b32 m0, s48
	s_nop 0
	global_load_lds_dwordx4 v[140:141], off
	v_lshl_add_u64 v[140:141], s[46:47], 0, v[134:135]
	s_add_i32 m0, s48, 0x2000
	s_nop 0
	global_load_lds_dwordx4 v[140:141], off
	v_lshl_add_u64 v[140:141], v[244:245], 0, s[42:43]
	s_mov_b32 m0, s76
	s_nop 0
	global_load_lds_dwordx4 v[140:141], off
	v_lshl_add_u64 v[140:141], v[246:247], 0, s[42:43]
	s_mov_b32 m0, s77
	s_nop 0
	global_load_lds_dwordx4 v[140:141], off
	s_waitcnt vmcnt(8)
	s_waitcnt lgkmcnt(0)
	s_setprio 1
	s_waitcnt lgkmcnt(0)
	v_mfma_f32_16x16x32_bf16 v[62:65], v[146:149], v[206:209], v[62:65]
	v_mfma_f32_16x16x32_bf16 v[58:61], v[154:157], v[206:209], v[58:61]
	v_mfma_f32_16x16x32_bf16 v[46:49], v[146:149], v[214:217], v[46:49]
	v_mfma_f32_16x16x32_bf16 v[42:45], v[154:157], v[214:217], v[42:45]
	s_barrier
	v_mfma_f32_16x16x32_bf16 v[30:33], v[146:149], v[222:225], v[30:33]
	v_mfma_f32_16x16x32_bf16 v[26:29], v[154:157], v[222:225], v[26:29]
	v_mfma_f32_16x16x32_bf16 v[14:17], v[146:149], v[230:233], v[14:17]
	v_mfma_f32_16x16x32_bf16 v[10:13], v[154:157], v[230:233], v[10:13]
	v_mfma_f32_16x16x32_bf16 v[62:65], v[150:153], v[210:213], v[62:65]
	v_mfma_f32_16x16x32_bf16 v[58:61], v[158:161], v[210:213], v[58:61]
	v_mfma_f32_16x16x32_bf16 v[46:49], v[150:153], v[218:221], v[46:49]
	v_mfma_f32_16x16x32_bf16 v[42:45], v[158:161], v[218:221], v[42:45]
	v_mfma_f32_16x16x32_bf16 v[30:33], v[150:153], v[226:229], v[30:33]
	v_mfma_f32_16x16x32_bf16 v[26:29], v[158:161], v[226:229], v[26:29]
	v_mfma_f32_16x16x32_bf16 v[14:17], v[150:153], v[234:237], v[14:17]
	v_mfma_f32_16x16x32_bf16 v[10:13], v[158:161], v[234:237], v[10:13]
	v_mfma_f32_16x16x32_bf16 v[54:57], v[162:165], v[206:209], v[54:57]
	v_mfma_f32_16x16x32_bf16 v[50:53], v[182:185], v[206:209], v[50:53]
	v_mfma_f32_16x16x32_bf16 v[38:41], v[162:165], v[214:217], v[38:41]
	v_mfma_f32_16x16x32_bf16 v[34:37], v[182:185], v[214:217], v[34:37]
	v_mfma_f32_16x16x32_bf16 v[22:25], v[162:165], v[222:225], v[22:25]
	v_mfma_f32_16x16x32_bf16 v[18:21], v[182:185], v[222:225], v[18:21]
	v_mfma_f32_16x16x32_bf16 v[6:9], v[162:165], v[230:233], v[6:9]
	v_mfma_f32_16x16x32_bf16 v[2:5], v[182:185], v[230:233], v[2:5]
	v_mfma_f32_16x16x32_bf16 v[54:57], v[178:181], v[210:213], v[54:57]
	v_mfma_f32_16x16x32_bf16 v[50:53], v[186:189], v[210:213], v[50:53]
	v_mfma_f32_16x16x32_bf16 v[38:41], v[178:181], v[218:221], v[38:41]
	v_mfma_f32_16x16x32_bf16 v[34:37], v[186:189], v[218:221], v[34:37]
	v_mfma_f32_16x16x32_bf16 v[22:25], v[178:181], v[226:229], v[22:25]
	v_mfma_f32_16x16x32_bf16 v[18:21], v[186:189], v[226:229], v[18:21]
	v_mfma_f32_16x16x32_bf16 v[6:9], v[178:181], v[234:237], v[6:9]
	v_mfma_f32_16x16x32_bf16 v[2:5], v[186:189], v[234:237], v[2:5]
	s_barrier
	s_setprio 0
	s_add_i32 s84, s84, 2
	s_add_u32 s64, s64, 0x100
	s_addc_u32 s65, s65, 0
	s_add_u32 s82, s82, 0x100
	s_addc_u32 s83, s83, 0
	s_cmp_gt_u32 s84, 29
	s_cbranch_scc0 .LBB0_1035
	s_and_b64 vcc, exec, s[10:11]
	s_cbranch_vccz .LBB0_1038
	s_barrier

.LBB0_1112:
	s_add_u32 s46, s64, 0xffe00080
	s_addc_u32 s47, s65, -1
	s_add_i32 s48, 0, 0x10000
	s_cmpk_eq_i32 s84, 0x7c
	s_cselect_b32 s67, s19, s47
	s_cselect_b32 s66, s80, s46
	s_cselect_b32 s61, s17, s83
	s_cselect_b32 s60, s81, s82
	s_add_i32 s49, 0, 0x14000
	v_add_u32_e32 v142, s48, v182
	v_add_u32_e32 v164, s49, v182
	ds_read_b128 v[130:133], v142
	ds_read_b128 v[134:137], v142 offset:1024
	ds_read_b128 v[138:141], v142 offset:2048
	ds_read_b128 v[142:145], v142 offset:3072
	ds_read_b128 v[146:149], v164
	ds_read_b128 v[160:163], v164 offset:1024
	ds_read_b128 v[178:181], v164 offset:2048
	ds_read_b128 v[186:189], v164 offset:3072
	v_lshl_add_u64 v[164:165], s[64:65], 0, v[156:157]
	s_add_i32 m0, s63, 0xc000
	ds_read_b128 v[206:209], v184
	ds_read_b128 v[210:213], v184 offset:1024
	ds_read_b128 v[214:217], v184 offset:2048
	ds_read_b128 v[218:221], v184 offset:3072
	ds_read_b128 v[222:225], v184 offset:4096
	ds_read_b128 v[226:229], v184 offset:5120
	ds_read_b128 v[230:233], v184 offset:6144
	ds_read_b128 v[234:237], v184 offset:7168
	global_load_lds_dwordx4 v[164:165], off
	v_lshl_add_u64 v[164:165], s[64:65], 0, v[158:159]
	s_add_i32 m0, s63, 0xe000
	s_nop 0
	global_load_lds_dwordx4 v[164:165], off
	s_waitcnt vmcnt(8)
	s_waitcnt lgkmcnt(0)
	s_setprio 1
	s_waitcnt lgkmcnt(0)
	v_mfma_f32_16x16x32_bf16 v[126:129], v[130:133], v[206:209], v[126:129]
	v_mfma_f32_16x16x32_bf16 v[122:125], v[138:141], v[206:209], v[122:125]
	v_mfma_f32_16x16x32_bf16 v[118:121], v[130:133], v[214:217], v[118:121]
	v_mfma_f32_16x16x32_bf16 v[114:117], v[138:141], v[214:217], v[114:117]
	s_barrier
	v_mfma_f32_16x16x32_bf16 v[94:97], v[130:133], v[222:225], v[94:97]
	v_mfma_f32_16x16x32_bf16 v[90:93], v[138:141], v[222:225], v[90:93]
	v_mfma_f32_16x16x32_bf16 v[82:85], v[130:133], v[230:233], v[82:85]
	v_mfma_f32_16x16x32_bf16 v[74:77], v[138:141], v[230:233], v[74:77]
	v_mfma_f32_16x16x32_bf16 v[126:129], v[134:137], v[210:213], v[126:129]
	v_mfma_f32_16x16x32_bf16 v[122:125], v[142:145], v[210:213], v[122:125]
	v_mfma_f32_16x16x32_bf16 v[118:121], v[134:137], v[218:221], v[118:121]
	v_mfma_f32_16x16x32_bf16 v[114:117], v[142:145], v[218:221], v[114:117]
	v_mfma_f32_16x16x32_bf16 v[94:97], v[134:137], v[226:229], v[94:97]
	v_mfma_f32_16x16x32_bf16 v[90:93], v[142:145], v[226:229], v[90:93]
	v_mfma_f32_16x16x32_bf16 v[82:85], v[134:137], v[234:237], v[82:85]
	v_mfma_f32_16x16x32_bf16 v[74:77], v[142:145], v[234:237], v[74:77]
	v_mfma_f32_16x16x32_bf16 v[110:113], v[146:149], v[206:209], v[110:113]
	v_mfma_f32_16x16x32_bf16 v[106:109], v[178:181], v[206:209], v[106:109]
	v_mfma_f32_16x16x32_bf16 v[102:105], v[146:149], v[214:217], v[102:105]
	v_mfma_f32_16x16x32_bf16 v[98:101], v[178:181], v[214:217], v[98:101]
	v_mfma_f32_16x16x32_bf16 v[86:89], v[146:149], v[222:225], v[86:89]
	v_mfma_f32_16x16x32_bf16 v[78:81], v[178:181], v[222:225], v[78:81]
	v_mfma_f32_16x16x32_bf16 v[70:73], v[146:149], v[230:233], v[70:73]
	v_mfma_f32_16x16x32_bf16 v[66:69], v[178:181], v[230:233], v[66:69]
	v_mfma_f32_16x16x32_bf16 v[110:113], v[160:163], v[210:213], v[110:113]
	v_mfma_f32_16x16x32_bf16 v[106:109], v[186:189], v[210:213], v[106:109]
	v_mfma_f32_16x16x32_bf16 v[102:105], v[160:163], v[218:221], v[102:105]
	v_mfma_f32_16x16x32_bf16 v[98:101], v[186:189], v[218:221], v[98:101]
	v_mfma_f32_16x16x32_bf16 v[86:89], v[160:163], v[226:229], v[86:89]
	v_mfma_f32_16x16x32_bf16 v[78:81], v[186:189], v[226:229], v[78:81]
	v_mfma_f32_16x16x32_bf16 v[70:73], v[160:163], v[234:237], v[70:73]
	v_mfma_f32_16x16x32_bf16 v[66:69], v[186:189], v[234:237], v[66:69]
	s_barrier
	s_setprio 0
	s_add_i32 s46, s48, s72
	v_lshl_add_u64 v[164:165], s[60:61], 0, v[166:167]
	s_mov_b32 m0, s46
	ds_read_b128 v[206:209], v184 offset:16384
	ds_read_b128 v[210:213], v184 offset:17408
	ds_read_b128 v[214:217], v184 offset:18432
	ds_read_b128 v[218:221], v184 offset:19456
	ds_read_b128 v[222:225], v184 offset:20480
	ds_read_b128 v[226:229], v184 offset:21504
	ds_read_b128 v[230:233], v184 offset:22528
	ds_read_b128 v[234:237], v184 offset:23552
	global_load_lds_dwordx4 v[164:165], off
	s_add_i32 m0, s46, 0x2000
	s_add_u32 s46, s60, 0x200000
	v_lshl_add_u64 v[242:243], s[60:61], 0, v[154:155]
	s_addc_u32 s47, s61, 0
	s_add_i32 s48, s49, s72
	global_load_lds_dwordx4 v[242:243], off
	v_lshl_add_u64 v[244:245], s[46:47], 0, v[166:167]
	s_mov_b32 m0, s48
	v_lshl_add_u64 v[246:247], s[66:67], 0, v[152:153]
	global_load_lds_dwordx4 v[244:245], off
	v_lshl_add_u64 v[244:245], s[46:47], 0, v[154:155]
	s_add_i32 m0, s48, 0x2000
	s_nop 0
	global_load_lds_dwordx4 v[244:245], off
	v_lshl_add_u64 v[244:245], s[66:67], 0, v[150:151]
	s_mov_b32 m0, s63
	s_nop 0
	global_load_lds_dwordx4 v[244:245], off
	s_mov_b32 m0, s73
	s_nop 0
	global_load_lds_dwordx4 v[246:247], off
	s_waitcnt vmcnt(8)
	s_waitcnt lgkmcnt(0)
	s_setprio 1
	s_waitcnt lgkmcnt(0)
	v_mfma_f32_16x16x32_bf16 v[62:65], v[130:133], v[206:209], v[62:65]
	v_mfma_f32_16x16x32_bf16 v[58:61], v[138:141], v[206:209], v[58:61]
	v_mfma_f32_16x16x32_bf16 v[50:53], v[130:133], v[214:217], v[50:53]
	v_mfma_f32_16x16x32_bf16 v[42:45], v[138:141], v[214:217], v[42:45]
	s_barrier
	v_mfma_f32_16x16x32_bf16 v[34:37], v[130:133], v[222:225], v[34:37]
	v_mfma_f32_16x16x32_bf16 v[26:29], v[138:141], v[222:225], v[26:29]
	v_mfma_f32_16x16x32_bf16 v[18:21], v[130:133], v[230:233], v[18:21]
	v_mfma_f32_16x16x32_bf16 v[10:13], v[138:141], v[230:233], v[10:13]
	v_mfma_f32_16x16x32_bf16 v[62:65], v[134:137], v[210:213], v[62:65]
	v_mfma_f32_16x16x32_bf16 v[58:61], v[142:145], v[210:213], v[58:61]
	v_mfma_f32_16x16x32_bf16 v[50:53], v[134:137], v[218:221], v[50:53]
	v_mfma_f32_16x16x32_bf16 v[42:45], v[142:145], v[218:221], v[42:45]
	v_mfma_f32_16x16x32_bf16 v[34:37], v[134:137], v[226:229], v[34:37]
	v_mfma_f32_16x16x32_bf16 v[26:29], v[142:145], v[226:229], v[26:29]
	v_mfma_f32_16x16x32_bf16 v[18:21], v[134:137], v[234:237], v[18:21]
	v_mfma_f32_16x16x32_bf16 v[10:13], v[142:145], v[234:237], v[10:13]
	v_mfma_f32_16x16x32_bf16 v[54:57], v[146:149], v[206:209], v[54:57]
	v_mfma_f32_16x16x32_bf16 v[46:49], v[178:181], v[206:209], v[46:49]
	v_mfma_f32_16x16x32_bf16 v[38:41], v[146:149], v[214:217], v[38:41]
	v_mfma_f32_16x16x32_bf16 v[30:33], v[178:181], v[214:217], v[30:33]
	v_mfma_f32_16x16x32_bf16 v[22:25], v[146:149], v[222:225], v[22:25]
	v_mfma_f32_16x16x32_bf16 v[14:17], v[178:181], v[222:225], v[14:17]
	v_mfma_f32_16x16x32_bf16 v[6:9], v[146:149], v[230:233], v[6:9]
	v_mfma_f32_16x16x32_bf16 v[2:5], v[178:181], v[230:233], v[2:5]
	v_mfma_f32_16x16x32_bf16 v[54:57], v[160:163], v[210:213], v[54:57]
	v_mfma_f32_16x16x32_bf16 v[46:49], v[186:189], v[210:213], v[46:49]
	v_mfma_f32_16x16x32_bf16 v[38:41], v[160:163], v[218:221], v[38:41]
	v_mfma_f32_16x16x32_bf16 v[30:33], v[186:189], v[218:221], v[30:33]
	v_mfma_f32_16x16x32_bf16 v[22:25], v[160:163], v[226:229], v[22:25]
	v_mfma_f32_16x16x32_bf16 v[14:17], v[186:189], v[226:229], v[14:17]
	v_mfma_f32_16x16x32_bf16 v[6:9], v[160:163], v[234:237], v[6:9]
	v_mfma_f32_16x16x32_bf16 v[2:5], v[186:189], v[234:237], v[2:5]
	s_barrier
	s_setprio 0
	s_add_i32 s48, 0, 0x18000
	s_add_i32 s49, 0, 0x1c000
	v_add_u32_e32 v142, s48, v182
	v_add_u32_e32 v185, s49, v182
	ds_read_b128 v[130:133], v142
	ds_read_b128 v[134:137], v142 offset:1024
	ds_read_b128 v[138:141], v142 offset:2048
	ds_read_b128 v[142:145], v142 offset:3072
	ds_read_b128 v[146:149], v185
	ds_read_b128 v[160:163], v185 offset:1024
	ds_read_b128 v[178:181], v185 offset:2048
	ds_read_b128 v[186:189], v185 offset:3072
	s_add_u32 s46, s66, 0x200000
	s_addc_u32 s47, s67, 0
	s_mov_b32 m0, s74
	v_lshl_add_u64 v[248:249], s[46:47], 0, v[150:151]
	ds_read_b128 v[206:209], v184 offset:32768
	ds_read_b128 v[210:213], v184 offset:33792
	ds_read_b128 v[214:217], v184 offset:34816
	ds_read_b128 v[218:221], v184 offset:35840
	ds_read_b128 v[222:225], v184 offset:36864
	ds_read_b128 v[226:229], v184 offset:37888
	ds_read_b128 v[230:233], v184 offset:38912
	ds_read_b128 v[234:237], v184 offset:39936
	global_load_lds_dwordx4 v[248:249], off
	v_lshl_add_u64 v[248:249], s[46:47], 0, v[152:153]
	s_mov_b32 m0, s75
	s_nop 0
	global_load_lds_dwordx4 v[248:249], off
	s_waitcnt vmcnt(8)
	s_waitcnt lgkmcnt(0)
	s_setprio 1
	s_waitcnt lgkmcnt(0)
	v_mfma_f32_16x16x32_bf16 v[126:129], v[130:133], v[206:209], v[126:129]
	v_mfma_f32_16x16x32_bf16 v[122:125], v[138:141], v[206:209], v[122:125]
	v_mfma_f32_16x16x32_bf16 v[118:121], v[130:133], v[214:217], v[118:121]
	v_mfma_f32_16x16x32_bf16 v[114:117], v[138:141], v[214:217], v[114:117]
	s_barrier
	v_mfma_f32_16x16x32_bf16 v[94:97], v[130:133], v[222:225], v[94:97]
	v_mfma_f32_16x16x32_bf16 v[90:93], v[138:141], v[222:225], v[90:93]
	v_mfma_f32_16x16x32_bf16 v[82:85], v[130:133], v[230:233], v[82:85]
	v_mfma_f32_16x16x32_bf16 v[74:77], v[138:141], v[230:233], v[74:77]
	v_mfma_f32_16x16x32_bf16 v[126:129], v[134:137], v[210:213], v[126:129]
	v_mfma_f32_16x16x32_bf16 v[122:125], v[142:145], v[210:213], v[122:125]
	v_mfma_f32_16x16x32_bf16 v[118:121], v[134:137], v[218:221], v[118:121]
	v_mfma_f32_16x16x32_bf16 v[114:117], v[142:145], v[218:221], v[114:117]
	v_mfma_f32_16x16x32_bf16 v[94:97], v[134:137], v[226:229], v[94:97]
	v_mfma_f32_16x16x32_bf16 v[90:93], v[142:145], v[226:229], v[90:93]
	v_mfma_f32_16x16x32_bf16 v[82:85], v[134:137], v[234:237], v[82:85]
	v_mfma_f32_16x16x32_bf16 v[74:77], v[142:145], v[234:237], v[74:77]
	v_mfma_f32_16x16x32_bf16 v[110:113], v[146:149], v[206:209], v[110:113]
	v_mfma_f32_16x16x32_bf16 v[106:109], v[178:181], v[206:209], v[106:109]
	v_mfma_f32_16x16x32_bf16 v[102:105], v[146:149], v[214:217], v[102:105]
	v_mfma_f32_16x16x32_bf16 v[98:101], v[178:181], v[214:217], v[98:101]
	v_mfma_f32_16x16x32_bf16 v[86:89], v[146:149], v[222:225], v[86:89]
	v_mfma_f32_16x16x32_bf16 v[78:81], v[178:181], v[222:225], v[78:81]
	v_mfma_f32_16x16x32_bf16 v[70:73], v[146:149], v[230:233], v[70:73]
	v_mfma_f32_16x16x32_bf16 v[66:69], v[178:181], v[230:233], v[66:69]
	v_mfma_f32_16x16x32_bf16 v[110:113], v[160:163], v[210:213], v[110:113]
	v_mfma_f32_16x16x32_bf16 v[106:109], v[186:189], v[210:213], v[106:109]
	v_mfma_f32_16x16x32_bf16 v[102:105], v[160:163], v[218:221], v[102:105]
	v_mfma_f32_16x16x32_bf16 v[98:101], v[186:189], v[218:221], v[98:101]
	v_mfma_f32_16x16x32_bf16 v[86:89], v[160:163], v[226:229], v[86:89]
	v_mfma_f32_16x16x32_bf16 v[78:81], v[186:189], v[226:229], v[78:81]
	v_mfma_f32_16x16x32_bf16 v[70:73], v[160:163], v[234:237], v[70:73]
	v_mfma_f32_16x16x32_bf16 v[66:69], v[186:189], v[234:237], v[66:69]
	s_barrier
	s_setprio 0
	s_add_i32 s46, s48, s72
	v_lshl_add_u64 v[164:165], v[164:165], 0, s[42:43]
	s_mov_b32 m0, s46
	ds_read_b128 v[206:209], v184 offset:49152
	ds_read_b128 v[210:213], v184 offset:50176
	ds_read_b128 v[214:217], v184 offset:51200
	ds_read_b128 v[218:221], v184 offset:52224
	ds_read_b128 v[222:225], v184 offset:53248
	ds_read_b128 v[226:229], v184 offset:54272
	ds_read_b128 v[230:233], v184 offset:55296
	ds_read_b128 v[234:237], v184 offset:56320
	global_load_lds_dwordx4 v[164:165], off
	s_add_i32 m0, s46, 0x2000
	s_add_u32 s46, s60, 0x200080
	v_lshl_add_u64 v[164:165], v[242:243], 0, s[42:43]
	s_addc_u32 s47, s61, 0
	s_add_i32 s48, s49, s72
	global_load_lds_dwordx4 v[164:165], off
	v_lshl_add_u64 v[164:165], s[46:47], 0, v[166:167]
	s_mov_b32 m0, s48
	s_nop 0
	global_load_lds_dwordx4 v[164:165], off
	v_lshl_add_u64 v[164:165], s[46:47], 0, v[154:155]
	s_add_i32 m0, s48, 0x2000
	s_nop 0
	global_load_lds_dwordx4 v[164:165], off
	v_lshl_add_u64 v[164:165], v[244:245], 0, s[42:43]
	s_mov_b32 m0, s76
	s_nop 0
	global_load_lds_dwordx4 v[164:165], off
	v_lshl_add_u64 v[164:165], v[246:247], 0, s[42:43]
	s_mov_b32 m0, s77
	s_nop 0
	global_load_lds_dwordx4 v[164:165], off
	s_waitcnt vmcnt(8)
	s_waitcnt lgkmcnt(0)
	s_setprio 1
	s_waitcnt lgkmcnt(0)
	v_mfma_f32_16x16x32_bf16 v[62:65], v[130:133], v[206:209], v[62:65]
	v_mfma_f32_16x16x32_bf16 v[58:61], v[138:141], v[206:209], v[58:61]
	v_mfma_f32_16x16x32_bf16 v[50:53], v[130:133], v[214:217], v[50:53]
	v_mfma_f32_16x16x32_bf16 v[42:45], v[138:141], v[214:217], v[42:45]
	s_barrier
	v_mfma_f32_16x16x32_bf16 v[34:37], v[130:133], v[222:225], v[34:37]
	v_mfma_f32_16x16x32_bf16 v[26:29], v[138:141], v[222:225], v[26:29]
	v_mfma_f32_16x16x32_bf16 v[18:21], v[130:133], v[230:233], v[18:21]
	v_mfma_f32_16x16x32_bf16 v[10:13], v[138:141], v[230:233], v[10:13]
	v_mfma_f32_16x16x32_bf16 v[62:65], v[134:137], v[210:213], v[62:65]
	v_mfma_f32_16x16x32_bf16 v[58:61], v[142:145], v[210:213], v[58:61]
	v_mfma_f32_16x16x32_bf16 v[50:53], v[134:137], v[218:221], v[50:53]
	v_mfma_f32_16x16x32_bf16 v[42:45], v[142:145], v[218:221], v[42:45]
	v_mfma_f32_16x16x32_bf16 v[34:37], v[134:137], v[226:229], v[34:37]
	v_mfma_f32_16x16x32_bf16 v[26:29], v[142:145], v[226:229], v[26:29]
	v_mfma_f32_16x16x32_bf16 v[18:21], v[134:137], v[234:237], v[18:21]
	v_mfma_f32_16x16x32_bf16 v[10:13], v[142:145], v[234:237], v[10:13]
	v_mfma_f32_16x16x32_bf16 v[54:57], v[146:149], v[206:209], v[54:57]
	v_mfma_f32_16x16x32_bf16 v[46:49], v[178:181], v[206:209], v[46:49]
	v_mfma_f32_16x16x32_bf16 v[38:41], v[146:149], v[214:217], v[38:41]
	v_mfma_f32_16x16x32_bf16 v[30:33], v[178:181], v[214:217], v[30:33]
	v_mfma_f32_16x16x32_bf16 v[22:25], v[146:149], v[222:225], v[22:25]
	v_mfma_f32_16x16x32_bf16 v[14:17], v[178:181], v[222:225], v[14:17]
	v_mfma_f32_16x16x32_bf16 v[6:9], v[146:149], v[230:233], v[6:9]
	v_mfma_f32_16x16x32_bf16 v[2:5], v[178:181], v[230:233], v[2:5]
	v_mfma_f32_16x16x32_bf16 v[54:57], v[160:163], v[210:213], v[54:57]
	v_mfma_f32_16x16x32_bf16 v[46:49], v[186:189], v[210:213], v[46:49]
	v_mfma_f32_16x16x32_bf16 v[38:41], v[160:163], v[218:221], v[38:41]
	v_mfma_f32_16x16x32_bf16 v[30:33], v[186:189], v[218:221], v[30:33]
	v_mfma_f32_16x16x32_bf16 v[22:25], v[160:163], v[226:229], v[22:25]
	v_mfma_f32_16x16x32_bf16 v[14:17], v[186:189], v[226:229], v[14:17]
	v_mfma_f32_16x16x32_bf16 v[6:9], v[160:163], v[234:237], v[6:9]
	v_mfma_f32_16x16x32_bf16 v[2:5], v[186:189], v[234:237], v[2:5]
	s_barrier
	s_setprio 0
	s_add_i32 s84, s84, 2
	s_add_u32 s64, s64, 0x100
	s_addc_u32 s65, s65, 0
	s_add_u32 s82, s82, 0x100
	s_addc_u32 s83, s83, 0
	s_cmpk_gt_u32 s84, 0x7d
	s_cbranch_scc0 .LBB0_1112
	s_and_b64 vcc, exec, s[12:13]
	s_cbranch_vccz .LBB0_1115
	s_barrier

.LBB0_1138:
	s_add_u32 s46, s62, 0xffe00080
	s_addc_u32 s47, s63, -1
	s_add_i32 s48, 0, 0x10000
	s_cmpk_eq_i32 s82, 0x7c
	s_cselect_b32 s65, s17, s47
	s_cselect_b32 s64, s78, s46
	s_cselect_b32 s61, s13, s81
	s_cselect_b32 s60, s79, s80
	s_add_i32 s49, 0, 0x14000
	v_add_u32_e32 v142, s48, v186
	v_add_u32_e32 v164, s49, v186
	ds_read_b128 v[130:133], v142
	ds_read_b128 v[134:137], v142 offset:1024
	ds_read_b128 v[138:141], v142 offset:2048
	ds_read_b128 v[142:145], v142 offset:3072
	ds_read_b128 v[146:149], v164
	ds_read_b128 v[160:163], v164 offset:1024
	ds_read_b128 v[178:181], v164 offset:2048
	ds_read_b128 v[182:185], v164 offset:3072
	v_lshl_add_u64 v[164:165], s[62:63], 0, v[156:157]
	s_add_i32 m0, s71, 0xc000
	ds_read_b128 v[206:209], v188
	ds_read_b128 v[210:213], v188 offset:1024
	ds_read_b128 v[214:217], v188 offset:2048
	ds_read_b128 v[218:221], v188 offset:3072
	ds_read_b128 v[222:225], v188 offset:4096
	ds_read_b128 v[226:229], v188 offset:5120
	ds_read_b128 v[230:233], v188 offset:6144
	ds_read_b128 v[234:237], v188 offset:7168
	global_load_lds_dwordx4 v[164:165], off
	v_lshl_add_u64 v[164:165], s[62:63], 0, v[158:159]
	s_add_i32 m0, s71, 0xe000
	s_nop 0
	global_load_lds_dwordx4 v[164:165], off
	s_waitcnt vmcnt(8)
	s_waitcnt lgkmcnt(0)
	s_setprio 1
	s_waitcnt lgkmcnt(0)
	v_mfma_f32_16x16x32_bf16 v[126:129], v[130:133], v[206:209], v[126:129]
	v_mfma_f32_16x16x32_bf16 v[122:125], v[138:141], v[206:209], v[122:125]
	v_mfma_f32_16x16x32_bf16 v[118:121], v[130:133], v[214:217], v[118:121]
	v_mfma_f32_16x16x32_bf16 v[110:113], v[138:141], v[214:217], v[110:113]
	s_barrier
	v_mfma_f32_16x16x32_bf16 v[94:97], v[130:133], v[222:225], v[94:97]
	v_mfma_f32_16x16x32_bf16 v[90:93], v[138:141], v[222:225], v[90:93]
	v_mfma_f32_16x16x32_bf16 v[82:85], v[130:133], v[230:233], v[82:85]
	v_mfma_f32_16x16x32_bf16 v[74:77], v[138:141], v[230:233], v[74:77]
	v_mfma_f32_16x16x32_bf16 v[126:129], v[134:137], v[210:213], v[126:129]
	v_mfma_f32_16x16x32_bf16 v[122:125], v[142:145], v[210:213], v[122:125]
	v_mfma_f32_16x16x32_bf16 v[118:121], v[134:137], v[218:221], v[118:121]
	v_mfma_f32_16x16x32_bf16 v[110:113], v[142:145], v[218:221], v[110:113]
	v_mfma_f32_16x16x32_bf16 v[94:97], v[134:137], v[226:229], v[94:97]
	v_mfma_f32_16x16x32_bf16 v[90:93], v[142:145], v[226:229], v[90:93]
	v_mfma_f32_16x16x32_bf16 v[82:85], v[134:137], v[234:237], v[82:85]
	v_mfma_f32_16x16x32_bf16 v[74:77], v[142:145], v[234:237], v[74:77]
	v_mfma_f32_16x16x32_bf16 v[114:117], v[146:149], v[206:209], v[114:117]
	v_mfma_f32_16x16x32_bf16 v[106:109], v[178:181], v[206:209], v[106:109]
	v_mfma_f32_16x16x32_bf16 v[102:105], v[146:149], v[214:217], v[102:105]
	v_mfma_f32_16x16x32_bf16 v[98:101], v[178:181], v[214:217], v[98:101]
	v_mfma_f32_16x16x32_bf16 v[86:89], v[146:149], v[222:225], v[86:89]
	v_mfma_f32_16x16x32_bf16 v[78:81], v[178:181], v[222:225], v[78:81]
	v_mfma_f32_16x16x32_bf16 v[70:73], v[146:149], v[230:233], v[70:73]
	v_mfma_f32_16x16x32_bf16 v[66:69], v[178:181], v[230:233], v[66:69]
	v_mfma_f32_16x16x32_bf16 v[114:117], v[160:163], v[210:213], v[114:117]
	v_mfma_f32_16x16x32_bf16 v[106:109], v[182:185], v[210:213], v[106:109]
	v_mfma_f32_16x16x32_bf16 v[102:105], v[160:163], v[218:221], v[102:105]
	v_mfma_f32_16x16x32_bf16 v[98:101], v[182:185], v[218:221], v[98:101]
	v_mfma_f32_16x16x32_bf16 v[86:89], v[160:163], v[226:229], v[86:89]
	v_mfma_f32_16x16x32_bf16 v[78:81], v[182:185], v[226:229], v[78:81]
	v_mfma_f32_16x16x32_bf16 v[70:73], v[160:163], v[234:237], v[70:73]
	v_mfma_f32_16x16x32_bf16 v[66:69], v[182:185], v[234:237], v[66:69]
	s_barrier
	s_setprio 0
	s_add_i32 s46, s48, s70
	v_lshl_add_u64 v[164:165], s[60:61], 0, v[166:167]
	s_mov_b32 m0, s46
	ds_read_b128 v[206:209], v188 offset:16384
	ds_read_b128 v[210:213], v188 offset:17408
	ds_read_b128 v[214:217], v188 offset:18432
	ds_read_b128 v[218:221], v188 offset:19456
	ds_read_b128 v[222:225], v188 offset:20480
	ds_read_b128 v[226:229], v188 offset:21504
	ds_read_b128 v[230:233], v188 offset:22528
	ds_read_b128 v[234:237], v188 offset:23552
	global_load_lds_dwordx4 v[164:165], off
	s_add_i32 m0, s46, 0x2000
	s_add_u32 s46, s60, 0x200000
	v_lshl_add_u64 v[242:243], s[60:61], 0, v[154:155]
	s_addc_u32 s47, s61, 0
	s_add_i32 s48, s49, s70
	global_load_lds_dwordx4 v[242:243], off
	v_lshl_add_u64 v[244:245], s[46:47], 0, v[166:167]
	s_mov_b32 m0, s48
	v_lshl_add_u64 v[246:247], s[64:65], 0, v[152:153]
	global_load_lds_dwordx4 v[244:245], off
	v_lshl_add_u64 v[244:245], s[46:47], 0, v[154:155]
	s_add_i32 m0, s48, 0x2000
	s_nop 0
	global_load_lds_dwordx4 v[244:245], off
	v_lshl_add_u64 v[244:245], s[64:65], 0, v[150:151]
	s_mov_b32 m0, s71
	s_nop 0
	global_load_lds_dwordx4 v[244:245], off
	s_mov_b32 m0, s72
	s_nop 0
	global_load_lds_dwordx4 v[246:247], off
	s_waitcnt vmcnt(8)
	s_waitcnt lgkmcnt(0)
	s_setprio 1
	s_waitcnt lgkmcnt(0)
	v_mfma_f32_16x16x32_bf16 v[62:65], v[130:133], v[206:209], v[62:65]
	v_mfma_f32_16x16x32_bf16 v[58:61], v[138:141], v[206:209], v[58:61]
	v_mfma_f32_16x16x32_bf16 v[50:53], v[130:133], v[214:217], v[50:53]
	v_mfma_f32_16x16x32_bf16 v[42:45], v[138:141], v[214:217], v[42:45]
	s_barrier
	v_mfma_f32_16x16x32_bf16 v[34:37], v[130:133], v[222:225], v[34:37]
	v_mfma_f32_16x16x32_bf16 v[26:29], v[138:141], v[222:225], v[26:29]
	v_mfma_f32_16x16x32_bf16 v[18:21], v[130:133], v[230:233], v[18:21]
	v_mfma_f32_16x16x32_bf16 v[10:13], v[138:141], v[230:233], v[10:13]
	v_mfma_f32_16x16x32_bf16 v[62:65], v[134:137], v[210:213], v[62:65]
	v_mfma_f32_16x16x32_bf16 v[58:61], v[142:145], v[210:213], v[58:61]
	v_mfma_f32_16x16x32_bf16 v[50:53], v[134:137], v[218:221], v[50:53]
	v_mfma_f32_16x16x32_bf16 v[42:45], v[142:145], v[218:221], v[42:45]
	v_mfma_f32_16x16x32_bf16 v[34:37], v[134:137], v[226:229], v[34:37]
	v_mfma_f32_16x16x32_bf16 v[26:29], v[142:145], v[226:229], v[26:29]
	v_mfma_f32_16x16x32_bf16 v[18:21], v[134:137], v[234:237], v[18:21]
	v_mfma_f32_16x16x32_bf16 v[10:13], v[142:145], v[234:237], v[10:13]
	v_mfma_f32_16x16x32_bf16 v[54:57], v[146:149], v[206:209], v[54:57]
	v_mfma_f32_16x16x32_bf16 v[46:49], v[178:181], v[206:209], v[46:49]
	v_mfma_f32_16x16x32_bf16 v[38:41], v[146:149], v[214:217], v[38:41]
	v_mfma_f32_16x16x32_bf16 v[30:33], v[178:181], v[214:217], v[30:33]
	v_mfma_f32_16x16x32_bf16 v[22:25], v[146:149], v[222:225], v[22:25]
	v_mfma_f32_16x16x32_bf16 v[14:17], v[178:181], v[222:225], v[14:17]
	v_mfma_f32_16x16x32_bf16 v[6:9], v[146:149], v[230:233], v[6:9]
	v_mfma_f32_16x16x32_bf16 v[2:5], v[178:181], v[230:233], v[2:5]
	v_mfma_f32_16x16x32_bf16 v[54:57], v[160:163], v[210:213], v[54:57]
	v_mfma_f32_16x16x32_bf16 v[46:49], v[182:185], v[210:213], v[46:49]
	v_mfma_f32_16x16x32_bf16 v[38:41], v[160:163], v[218:221], v[38:41]
	v_mfma_f32_16x16x32_bf16 v[30:33], v[182:185], v[218:221], v[30:33]
	v_mfma_f32_16x16x32_bf16 v[22:25], v[160:163], v[226:229], v[22:25]
	v_mfma_f32_16x16x32_bf16 v[14:17], v[182:185], v[226:229], v[14:17]
	v_mfma_f32_16x16x32_bf16 v[6:9], v[160:163], v[234:237], v[6:9]
	v_mfma_f32_16x16x32_bf16 v[2:5], v[182:185], v[234:237], v[2:5]
	s_barrier
	s_setprio 0
	s_add_i32 s48, 0, 0x18000
	s_add_i32 s49, 0, 0x1c000
	v_add_u32_e32 v142, s48, v186
	v_add_u32_e32 v182, s49, v186
	ds_read_b128 v[130:133], v142
	ds_read_b128 v[134:137], v142 offset:1024
	ds_read_b128 v[138:141], v142 offset:2048
	ds_read_b128 v[142:145], v142 offset:3072
	ds_read_b128 v[146:149], v182
	ds_read_b128 v[160:163], v182 offset:1024
	ds_read_b128 v[178:181], v182 offset:2048
	ds_read_b128 v[182:185], v182 offset:3072
	s_add_u32 s46, s64, 0x200000
	s_addc_u32 s47, s65, 0
	s_mov_b32 m0, s73
	v_lshl_add_u64 v[248:249], s[46:47], 0, v[150:151]
	ds_read_b128 v[206:209], v188 offset:32768
	ds_read_b128 v[210:213], v188 offset:33792
	ds_read_b128 v[214:217], v188 offset:34816
	ds_read_b128 v[218:221], v188 offset:35840
	ds_read_b128 v[222:225], v188 offset:36864
	ds_read_b128 v[226:229], v188 offset:37888
	ds_read_b128 v[230:233], v188 offset:38912
	ds_read_b128 v[234:237], v188 offset:39936
	global_load_lds_dwordx4 v[248:249], off
	v_lshl_add_u64 v[248:249], s[46:47], 0, v[152:153]
	s_mov_b32 m0, s74
	s_nop 0
	global_load_lds_dwordx4 v[248:249], off
	s_waitcnt vmcnt(8)
	s_waitcnt lgkmcnt(0)
	s_setprio 1
	s_waitcnt lgkmcnt(0)
	v_mfma_f32_16x16x32_bf16 v[126:129], v[130:133], v[206:209], v[126:129]
	v_mfma_f32_16x16x32_bf16 v[122:125], v[138:141], v[206:209], v[122:125]
	v_mfma_f32_16x16x32_bf16 v[118:121], v[130:133], v[214:217], v[118:121]
	v_mfma_f32_16x16x32_bf16 v[110:113], v[138:141], v[214:217], v[110:113]
	s_barrier
	v_mfma_f32_16x16x32_bf16 v[94:97], v[130:133], v[222:225], v[94:97]
	v_mfma_f32_16x16x32_bf16 v[90:93], v[138:141], v[222:225], v[90:93]
	v_mfma_f32_16x16x32_bf16 v[82:85], v[130:133], v[230:233], v[82:85]
	v_mfma_f32_16x16x32_bf16 v[74:77], v[138:141], v[230:233], v[74:77]
	v_mfma_f32_16x16x32_bf16 v[126:129], v[134:137], v[210:213], v[126:129]
	v_mfma_f32_16x16x32_bf16 v[122:125], v[142:145], v[210:213], v[122:125]
	v_mfma_f32_16x16x32_bf16 v[118:121], v[134:137], v[218:221], v[118:121]
	v_mfma_f32_16x16x32_bf16 v[110:113], v[142:145], v[218:221], v[110:113]
	v_mfma_f32_16x16x32_bf16 v[94:97], v[134:137], v[226:229], v[94:97]
	v_mfma_f32_16x16x32_bf16 v[90:93], v[142:145], v[226:229], v[90:93]
	v_mfma_f32_16x16x32_bf16 v[82:85], v[134:137], v[234:237], v[82:85]
	v_mfma_f32_16x16x32_bf16 v[74:77], v[142:145], v[234:237], v[74:77]
	v_mfma_f32_16x16x32_bf16 v[114:117], v[146:149], v[206:209], v[114:117]
	v_mfma_f32_16x16x32_bf16 v[106:109], v[178:181], v[206:209], v[106:109]
	v_mfma_f32_16x16x32_bf16 v[102:105], v[146:149], v[214:217], v[102:105]
	v_mfma_f32_16x16x32_bf16 v[98:101], v[178:181], v[214:217], v[98:101]
	v_mfma_f32_16x16x32_bf16 v[86:89], v[146:149], v[222:225], v[86:89]
	v_mfma_f32_16x16x32_bf16 v[78:81], v[178:181], v[222:225], v[78:81]
	v_mfma_f32_16x16x32_bf16 v[70:73], v[146:149], v[230:233], v[70:73]
	v_mfma_f32_16x16x32_bf16 v[66:69], v[178:181], v[230:233], v[66:69]
	v_mfma_f32_16x16x32_bf16 v[114:117], v[160:163], v[210:213], v[114:117]
	v_mfma_f32_16x16x32_bf16 v[106:109], v[182:185], v[210:213], v[106:109]
	v_mfma_f32_16x16x32_bf16 v[102:105], v[160:163], v[218:221], v[102:105]
	v_mfma_f32_16x16x32_bf16 v[98:101], v[182:185], v[218:221], v[98:101]
	v_mfma_f32_16x16x32_bf16 v[86:89], v[160:163], v[226:229], v[86:89]
	v_mfma_f32_16x16x32_bf16 v[78:81], v[182:185], v[226:229], v[78:81]
	v_mfma_f32_16x16x32_bf16 v[70:73], v[160:163], v[234:237], v[70:73]
	v_mfma_f32_16x16x32_bf16 v[66:69], v[182:185], v[234:237], v[66:69]
	s_barrier
	s_setprio 0
	s_add_i32 s46, s48, s70
	v_lshl_add_u64 v[164:165], v[164:165], 0, s[42:43]
	s_mov_b32 m0, s46
	ds_read_b128 v[206:209], v188 offset:49152
	ds_read_b128 v[210:213], v188 offset:50176
	ds_read_b128 v[214:217], v188 offset:51200
	ds_read_b128 v[218:221], v188 offset:52224
	ds_read_b128 v[222:225], v188 offset:53248
	ds_read_b128 v[226:229], v188 offset:54272
	ds_read_b128 v[230:233], v188 offset:55296
	ds_read_b128 v[234:237], v188 offset:56320
	global_load_lds_dwordx4 v[164:165], off
	s_add_i32 m0, s46, 0x2000
	s_add_u32 s46, s60, 0x200080
	v_lshl_add_u64 v[164:165], v[242:243], 0, s[42:43]
	s_addc_u32 s47, s61, 0
	s_add_i32 s48, s49, s70
	global_load_lds_dwordx4 v[164:165], off
	v_lshl_add_u64 v[164:165], s[46:47], 0, v[166:167]
	s_mov_b32 m0, s48
	s_nop 0
	global_load_lds_dwordx4 v[164:165], off
	v_lshl_add_u64 v[164:165], s[46:47], 0, v[154:155]
	s_add_i32 m0, s48, 0x2000
	s_nop 0
	global_load_lds_dwordx4 v[164:165], off
	v_lshl_add_u64 v[164:165], v[244:245], 0, s[42:43]
	s_mov_b32 m0, s75
	s_nop 0
	global_load_lds_dwordx4 v[164:165], off
	v_lshl_add_u64 v[164:165], v[246:247], 0, s[42:43]
	s_mov_b32 m0, s76
	s_nop 0
	global_load_lds_dwordx4 v[164:165], off
	s_waitcnt vmcnt(8)
	s_waitcnt lgkmcnt(0)
	s_setprio 1
	s_waitcnt lgkmcnt(0)
	v_mfma_f32_16x16x32_bf16 v[62:65], v[130:133], v[206:209], v[62:65]
	v_mfma_f32_16x16x32_bf16 v[58:61], v[138:141], v[206:209], v[58:61]
	v_mfma_f32_16x16x32_bf16 v[50:53], v[130:133], v[214:217], v[50:53]
	v_mfma_f32_16x16x32_bf16 v[42:45], v[138:141], v[214:217], v[42:45]
	s_barrier
	v_mfma_f32_16x16x32_bf16 v[34:37], v[130:133], v[222:225], v[34:37]
	v_mfma_f32_16x16x32_bf16 v[26:29], v[138:141], v[222:225], v[26:29]
	v_mfma_f32_16x16x32_bf16 v[18:21], v[130:133], v[230:233], v[18:21]
	v_mfma_f32_16x16x32_bf16 v[10:13], v[138:141], v[230:233], v[10:13]
	v_mfma_f32_16x16x32_bf16 v[62:65], v[134:137], v[210:213], v[62:65]
	v_mfma_f32_16x16x32_bf16 v[58:61], v[142:145], v[210:213], v[58:61]
	v_mfma_f32_16x16x32_bf16 v[50:53], v[134:137], v[218:221], v[50:53]
	v_mfma_f32_16x16x32_bf16 v[42:45], v[142:145], v[218:221], v[42:45]
	v_mfma_f32_16x16x32_bf16 v[34:37], v[134:137], v[226:229], v[34:37]
	v_mfma_f32_16x16x32_bf16 v[26:29], v[142:145], v[226:229], v[26:29]
	v_mfma_f32_16x16x32_bf16 v[18:21], v[134:137], v[234:237], v[18:21]
	v_mfma_f32_16x16x32_bf16 v[10:13], v[142:145], v[234:237], v[10:13]
	v_mfma_f32_16x16x32_bf16 v[54:57], v[146:149], v[206:209], v[54:57]
	v_mfma_f32_16x16x32_bf16 v[46:49], v[178:181], v[206:209], v[46:49]
	v_mfma_f32_16x16x32_bf16 v[38:41], v[146:149], v[214:217], v[38:41]
	v_mfma_f32_16x16x32_bf16 v[30:33], v[178:181], v[214:217], v[30:33]
	v_mfma_f32_16x16x32_bf16 v[22:25], v[146:149], v[222:225], v[22:25]
	v_mfma_f32_16x16x32_bf16 v[14:17], v[178:181], v[222:225], v[14:17]
	v_mfma_f32_16x16x32_bf16 v[6:9], v[146:149], v[230:233], v[6:9]
	v_mfma_f32_16x16x32_bf16 v[2:5], v[178:181], v[230:233], v[2:5]
	v_mfma_f32_16x16x32_bf16 v[54:57], v[160:163], v[210:213], v[54:57]
	v_mfma_f32_16x16x32_bf16 v[46:49], v[182:185], v[210:213], v[46:49]
	v_mfma_f32_16x16x32_bf16 v[38:41], v[160:163], v[218:221], v[38:41]
	v_mfma_f32_16x16x32_bf16 v[30:33], v[182:185], v[218:221], v[30:33]
	v_mfma_f32_16x16x32_bf16 v[22:25], v[160:163], v[226:229], v[22:25]
	v_mfma_f32_16x16x32_bf16 v[14:17], v[182:185], v[226:229], v[14:17]
	v_mfma_f32_16x16x32_bf16 v[6:9], v[160:163], v[234:237], v[6:9]
	v_mfma_f32_16x16x32_bf16 v[2:5], v[182:185], v[234:237], v[2:5]
	s_barrier
	s_setprio 0
	s_add_i32 s82, s82, 2
	s_add_u32 s62, s62, 0x100
	s_addc_u32 s63, s63, 0
	s_add_u32 s80, s80, 0x100
	s_addc_u32 s81, s81, 0
	s_cmpk_gt_u32 s82, 0x7d
	s_cbranch_scc0 .LBB0_1138
	s_and_b64 vcc, exec, s[10:11]
	s_cbranch_vccz .LBB0_1141
	s_barrier
